# GEMM K-loops: redundant post-barrier lgkmcnt(0) removed, vmcnt/lgkmcnt waits merged
# baseline (speedup 1.0000x reference)
; #define PG8_STAGE(bufoff, gbase, voff) do { _Pragma("unroll") for (int _i = 0; _i < 2; ++_i) \
;         __builtin_amdgcn_global_load_lds((const unsigned*)((const char*)(gbase) + (voff)[_i]), (PG8_LAS unsigned*)(lds + (bufoff) + ldsw + _i * 8192), 16, 0, 0); } while (0)
; #define PG8_LDA(dst, b, h) do { _Pragma("unroll") for (int m = 0; m < 4; ++m) _Pragma("unroll") for (int k = 0; k < 2; ++k) dst[m][k] = *(const PG8_LAS bf16x8*)(lds + PG8_SA(b, h) + aoff + m * 2048 + k * 1024); } while (0)
; #define PG8_LDB(dst, b, h) do { _Pragma("unroll") for (int n = 0; n < 2; ++n) _Pragma("unroll") for (int k = 0; k < 2; ++k) dst[n][k] = *(const PG8_LAS bf16x8*)(lds + PG8_SB(b, h) + boff + n * 2048 + k * 1024); } while (0)
; #define PG8_MMA(ai, bj, At, Bt) do { __builtin_amdgcn_s_setprio(1); _Pragma("unroll") for (int m = 0; m < 4; ++m) _Pragma("unroll") for (int n = 0; n < 2; ++n) _Pragma("unroll") for (int k = 0; k < 2; ++k) \
;         acc[ai][bj][m][n] = mma16<F16>(Bt[n][k], At[m][k], acc[ai][bj][m][n]); __builtin_amdgcn_s_setprio(0); } while (0)
; #define PG8_WAIT_V(n) asm volatile("s_waitcnt vmcnt(" #n ")" ::: "memory")
; #define PG8_WAIT_L(n) asm volatile("s_waitcnt lgkmcnt(" #n ")" ::: "memory")
; #define PG8_BAR __builtin_amdgcn_s_barrier()
; #define PG8_SCHED __builtin_amdgcn_sched_barrier(0)
; template <class Epi, class Sched, bool ALIGN_EPI = false, bool SP2 = false, bool F16 = false>
; __device__ __forceinline__ void gemm_phase(PG8_LAS unsigned char* lds, const Gemm g, const Sched& S, const Epi& E) {
;     ...
;             const char* a1 = cA + (size_t)(t + 1) * kstep;
;             const char* a2 = last ? nA : cA + (size_t)(t + 2) * kstep; const char* b2 = last ? nB : cB + (size_t)(t + 2) * kstep;
;             const char* a3 = a2 + kstep; const char* b3 = b2 + kstep;
;             if (last && has_next) S.a_ready(nxt);
;             if constexpr (SP2) {
;             PG8_LDB(B0, 0, 0); PG8_LDB(B1, 0, 1); PG8_SCHED; PG8_LDA(At, 0, 0); PG8_STAGE(PG8_SA(1, 1), a1 + hstep, voffA);
;             PG8_WAIT_V(8); PG8_WAIT_L(0); PG8_BAR; PG8_MMA(0, 0, At, B0); PG8_MMA(0, 1, At, B1); PG8_BAR; PG8_SCHED;
;             PG8_LDA(At, 0, 1); PG8_STAGE(PG8_SB(0, 0), b2, voffB); PG8_STAGE(PG8_SB(0, 1), b2 + hstep, voffB); PG8_STAGE(PG8_SA(0, 0), a2, voffA);
;             PG8_WAIT_V(8); PG8_WAIT_L(0); PG8_BAR; PG8_MMA(1, 0, At, B0); PG8_MMA(1, 1, At, B1); PG8_BAR; PG8_SCHED;
.LBB0_256:
	s_add_u32 s42, s0, 0xfffc0080
	s_addc_u32 s43, s1, -1
	s_add_i32 s68, 0, 0x10000
	s_cmp_eq_u32 s67, 12
	s_cselect_b32 s55, s4, s43
	s_cselect_b32 s54, s5, s42
	s_cselect_b32 s43, s7, s61
	s_cselect_b32 s42, s34, s59
	s_add_i32 s70, 0, 0x14000
	ds_read_b128 v[130:133], v242
	ds_read_b128 v[134:137], v242 offset:1024
	ds_read_b128 v[138:141], v242 offset:2048
	ds_read_b128 v[162:165], v242 offset:3072
	ds_read_b128 v[166:169], v242 offset:16384
	ds_read_b128 v[170:173], v242 offset:17408
	ds_read_b128 v[186:189], v242 offset:18432
	ds_read_b128 v[190:193], v242 offset:19456
	s_add_i32 m0, s21, 0xc000
	ds_read_b128 v[194:197], v240
	ds_read_b128 v[198:201], v240 offset:1024
	ds_read_b128 v[202:205], v240 offset:2048
	ds_read_b128 v[206:209], v240 offset:3072
	ds_read_b128 v[210:213], v240 offset:4096
	ds_read_b128 v[214:217], v240 offset:5120
	ds_read_b128 v[218:221], v240 offset:6144
	ds_read_b128 v[222:225], v240 offset:7168
	global_load_lds_dwordx4 v154, s[0:1]
	s_add_i32 m0, s21, 0xe000
	s_nop 0
	global_load_lds_dwordx4 v156, s[0:1]
	s_waitcnt vmcnt(8) lgkmcnt(0)
	s_barrier
	s_setprio 1
	v_mfma_f32_16x16x32_f16 v[124:127], v[130:133], v[194:197], v[124:127]
	v_mfma_f32_16x16x32_f16 v[120:123], v[138:141], v[194:197], v[120:123]
	v_mfma_f32_16x16x32_f16 v[116:119], v[130:133], v[202:205], v[116:119]
	v_mfma_f32_16x16x32_f16 v[112:115], v[138:141], v[202:205], v[112:115]
	v_mfma_f32_16x16x32_f16 v[108:111], v[130:133], v[210:213], v[108:111]
	v_mfma_f32_16x16x32_f16 v[104:107], v[138:141], v[210:213], v[104:107]
	v_mfma_f32_16x16x32_f16 v[100:103], v[130:133], v[218:221], v[100:103]
	v_mfma_f32_16x16x32_f16 v[96:99], v[138:141], v[218:221], v[96:99]
	v_mfma_f32_16x16x32_f16 v[124:127], v[134:137], v[198:201], v[124:127]
	v_mfma_f32_16x16x32_f16 v[120:123], v[162:165], v[198:201], v[120:123]
	v_mfma_f32_16x16x32_f16 v[116:119], v[134:137], v[206:209], v[116:119]
	v_mfma_f32_16x16x32_f16 v[112:115], v[162:165], v[206:209], v[112:115]
	v_mfma_f32_16x16x32_f16 v[108:111], v[134:137], v[214:217], v[108:111]
	v_mfma_f32_16x16x32_f16 v[104:107], v[162:165], v[214:217], v[104:107]
	v_mfma_f32_16x16x32_f16 v[100:103], v[134:137], v[222:225], v[100:103]
	v_mfma_f32_16x16x32_f16 v[96:99], v[162:165], v[222:225], v[96:99]
	v_mfma_f32_16x16x32_f16 v[60:63], v[166:169], v[194:197], v[60:63]
	v_mfma_f32_16x16x32_f16 v[56:59], v[186:189], v[194:197], v[56:59]
	v_mfma_f32_16x16x32_f16 v[52:55], v[166:169], v[202:205], v[52:55]
	v_mfma_f32_16x16x32_f16 v[48:51], v[186:189], v[202:205], v[48:51]
	v_mfma_f32_16x16x32_f16 v[44:47], v[166:169], v[210:213], v[44:47]
	v_mfma_f32_16x16x32_f16 v[40:43], v[186:189], v[210:213], v[40:43]
	v_mfma_f32_16x16x32_f16 v[36:39], v[166:169], v[218:221], v[36:39]
	v_mfma_f32_16x16x32_f16 v[32:35], v[186:189], v[218:221], v[32:35]
	v_mfma_f32_16x16x32_f16 v[60:63], v[170:173], v[198:201], v[60:63]
	v_mfma_f32_16x16x32_f16 v[56:59], v[190:193], v[198:201], v[56:59]
	v_mfma_f32_16x16x32_f16 v[52:55], v[170:173], v[206:209], v[52:55]
	v_mfma_f32_16x16x32_f16 v[48:51], v[190:193], v[206:209], v[48:51]
	v_mfma_f32_16x16x32_f16 v[44:47], v[170:173], v[214:217], v[44:47]
	v_mfma_f32_16x16x32_f16 v[40:43], v[190:193], v[214:217], v[40:43]
	v_mfma_f32_16x16x32_f16 v[36:39], v[170:173], v[222:225], v[36:39]
	v_mfma_f32_16x16x32_f16 v[32:35], v[190:193], v[222:225], v[32:35]
	s_setprio 0
	s_barrier
	s_add_u32 s98, s42, s16
	s_addc_u32 s99, s43, s17
	s_add_u32 s100, s54, s16
	s_addc_u32 s101, s55, s17
	s_add_i32 s68, s68, s20
	s_mov_b32 m0, s68
	ds_read_b128 v[194:197], v240 offset:16384
	ds_read_b128 v[198:201], v240 offset:17408
	ds_read_b128 v[202:205], v240 offset:18432
	ds_read_b128 v[206:209], v240 offset:19456
	ds_read_b128 v[210:213], v240 offset:20480
	ds_read_b128 v[214:217], v240 offset:21504
	ds_read_b128 v[218:221], v240 offset:22528
	ds_read_b128 v[222:225], v240 offset:23552
	global_load_lds_dwordx4 v146, s[42:43]
	s_add_i32 m0, s68, 0x2000
	s_add_u32 s68, s42, 0x40000
	s_addc_u32 s69, s43, 0
	s_add_i32 s70, s70, s20
	global_load_lds_dwordx4 v142, s[42:43]
	s_mov_b32 m0, s70
	s_nop 0
	global_load_lds_dwordx4 v146, s[68:69]
	s_add_i32 m0, s70, 0x2000
	s_nop 0
	global_load_lds_dwordx4 v142, s[68:69]
	s_mov_b32 m0, s21
	s_nop 0
	global_load_lds_dwordx4 v148, s[54:55]
	s_mov_b32 m0, s14
	s_nop 0
	global_load_lds_dwordx4 v144, s[54:55]
	s_waitcnt vmcnt(8) lgkmcnt(0)
	s_barrier
	s_setprio 1
	v_mfma_f32_16x16x32_f16 v[92:95], v[130:133], v[194:197], v[92:95]
	v_mfma_f32_16x16x32_f16 v[88:91], v[138:141], v[194:197], v[88:91]
	v_mfma_f32_16x16x32_f16 v[84:87], v[130:133], v[202:205], v[84:87]
	v_mfma_f32_16x16x32_f16 v[80:83], v[138:141], v[202:205], v[80:83]
	v_mfma_f32_16x16x32_f16 v[76:79], v[130:133], v[210:213], v[76:79]
	v_mfma_f32_16x16x32_f16 v[72:75], v[138:141], v[210:213], v[72:75]
	v_mfma_f32_16x16x32_f16 v[68:71], v[130:133], v[218:221], v[68:71]
	v_mfma_f32_16x16x32_f16 v[64:67], v[138:141], v[218:221], v[64:67]
	v_mfma_f32_16x16x32_f16 v[92:95], v[134:137], v[198:201], v[92:95]
	v_mfma_f32_16x16x32_f16 v[88:91], v[162:165], v[198:201], v[88:91]
	v_mfma_f32_16x16x32_f16 v[84:87], v[134:137], v[206:209], v[84:87]
	v_mfma_f32_16x16x32_f16 v[80:83], v[162:165], v[206:209], v[80:83]
	v_mfma_f32_16x16x32_f16 v[76:79], v[134:137], v[214:217], v[76:79]
	v_mfma_f32_16x16x32_f16 v[72:75], v[162:165], v[214:217], v[72:75]
	v_mfma_f32_16x16x32_f16 v[68:71], v[134:137], v[222:225], v[68:71]
	v_mfma_f32_16x16x32_f16 v[64:67], v[162:165], v[222:225], v[64:67]
	v_mfma_f32_16x16x32_f16 v[28:31], v[166:169], v[194:197], v[28:31]
	v_mfma_f32_16x16x32_f16 v[24:27], v[186:189], v[194:197], v[24:27]
	v_mfma_f32_16x16x32_f16 v[20:23], v[166:169], v[202:205], v[20:23]
	v_mfma_f32_16x16x32_f16 v[16:19], v[186:189], v[202:205], v[16:19]
	v_mfma_f32_16x16x32_f16 v[12:15], v[166:169], v[210:213], v[12:15]
	v_mfma_f32_16x16x32_f16 v[8:11], v[186:189], v[210:213], v[8:11]
	v_mfma_f32_16x16x32_f16 v[4:7], v[166:169], v[218:221], v[4:7]
	v_mfma_f32_16x16x32_f16 v[0:3], v[186:189], v[218:221], v[0:3]
	v_mfma_f32_16x16x32_f16 v[28:31], v[170:173], v[198:201], v[28:31]
	v_mfma_f32_16x16x32_f16 v[24:27], v[190:193], v[198:201], v[24:27]
	v_mfma_f32_16x16x32_f16 v[20:23], v[170:173], v[206:209], v[20:23]
	v_mfma_f32_16x16x32_f16 v[16:19], v[190:193], v[206:209], v[16:19]
	v_mfma_f32_16x16x32_f16 v[12:15], v[170:173], v[214:217], v[12:15]
	v_mfma_f32_16x16x32_f16 v[8:11], v[190:193], v[214:217], v[8:11]
	v_mfma_f32_16x16x32_f16 v[4:7], v[170:173], v[222:225], v[4:7]
	v_mfma_f32_16x16x32_f16 v[0:3], v[190:193], v[222:225], v[0:3]
	s_setprio 0
	s_barrier
; #define PG8_STAGE(bufoff, gbase, voff) do { _Pragma("unroll") for (int _i = 0; _i < 2; ++_i) \
;         __builtin_amdgcn_global_load_lds((const unsigned*)((const char*)(gbase) + (voff)[_i]), (PG8_LAS unsigned*)(lds + (bufoff) + ldsw + _i * 8192), 16, 0, 0); } while (0)
; #define PG8_LDA(dst, b, h) do { _Pragma("unroll") for (int m = 0; m < 4; ++m) _Pragma("unroll") for (int k = 0; k < 2; ++k) dst[m][k] = *(const PG8_LAS bf16x8*)(lds + PG8_SA(b, h) + aoff + m * 2048 + k * 1024); } while (0)
; #define PG8_LDB(dst, b, h) do { _Pragma("unroll") for (int n = 0; n < 2; ++n) _Pragma("unroll") for (int k = 0; k < 2; ++k) dst[n][k] = *(const PG8_LAS bf16x8*)(lds + PG8_SB(b, h) + boff + n * 2048 + k * 1024); } while (0)
; #define PG8_MMA(ai, bj, At, Bt) do { __builtin_amdgcn_s_setprio(1); _Pragma("unroll") for (int m = 0; m < 4; ++m) _Pragma("unroll") for (int n = 0; n < 2; ++n) _Pragma("unroll") for (int k = 0; k < 2; ++k) \
;         acc[ai][bj][m][n] = mma16<F16>(Bt[n][k], At[m][k], acc[ai][bj][m][n]); __builtin_amdgcn_s_setprio(0); } while (0)
; #define PG8_WAIT_V(n) asm volatile("s_waitcnt vmcnt(" #n ")" ::: "memory")
; #define PG8_WAIT_L(n) asm volatile("s_waitcnt lgkmcnt(" #n ")" ::: "memory")
; #define PG8_BAR __builtin_amdgcn_s_barrier()
; #define PG8_SCHED __builtin_amdgcn_sched_barrier(0)
; template <class Epi, class Sched, bool ALIGN_EPI = false, bool SP2 = false, bool F16 = false>
; __device__ __forceinline__ void gemm_phase(PG8_LAS unsigned char* lds, const Gemm g, const Sched& S, const Epi& E) {
;     ...
;             PG8_LDB(B0, 1, 0); PG8_LDB(B1, 1, 1); PG8_SCHED; PG8_LDA(At, 1, 0); PG8_STAGE(PG8_SA(0, 1), a2 + hstep, voffA);
;             PG8_WAIT_V(8); PG8_WAIT_L(0); PG8_BAR; PG8_MMA(0, 0, At, B0); PG8_MMA(0, 1, At, B1); PG8_BAR; PG8_SCHED;
;             PG8_LDA(At, 1, 1); PG8_STAGE(PG8_SB(1, 0), b3, voffB); PG8_STAGE(PG8_SB(1, 1), b3 + hstep, voffB); PG8_STAGE(PG8_SA(1, 0), a3, voffA);
;             PG8_WAIT_V(8); PG8_WAIT_L(0); PG8_BAR; PG8_MMA(1, 0, At, B0); PG8_MMA(1, 1, At, B1); PG8_BAR; PG8_SCHED;
	s_add_i32 s68, 0, 0x18000
	s_add_i32 s69, 0, 0x1c000
	ds_read_b128 v[130:133], v242 offset:32768
	ds_read_b128 v[134:137], v242 offset:33792
	ds_read_b128 v[138:141], v242 offset:34816
	ds_read_b128 v[162:165], v242 offset:35840
	ds_read_b128 v[166:169], v242 offset:49152
	ds_read_b128 v[170:173], v242 offset:50176
	ds_read_b128 v[186:189], v242 offset:51200
	ds_read_b128 v[190:193], v242 offset:52224
	s_add_u32 s54, s54, 0x40000
	s_addc_u32 s55, s55, 0
	s_mov_b32 m0, s15
	ds_read_b128 v[194:197], v240 offset:32768
	ds_read_b128 v[198:201], v240 offset:33792
	ds_read_b128 v[202:205], v240 offset:34816
	ds_read_b128 v[206:209], v240 offset:35840
	ds_read_b128 v[210:213], v240 offset:36864
	ds_read_b128 v[214:217], v240 offset:37888
	ds_read_b128 v[218:221], v240 offset:38912
	ds_read_b128 v[222:225], v240 offset:39936
	global_load_lds_dwordx4 v148, s[54:55]
	s_mov_b32 m0, s37
	s_nop 0
	global_load_lds_dwordx4 v144, s[54:55]
	s_waitcnt vmcnt(8) lgkmcnt(0)
	s_barrier
	s_setprio 1
	v_mfma_f32_16x16x32_f16 v[124:127], v[130:133], v[194:197], v[124:127]
	v_mfma_f32_16x16x32_f16 v[120:123], v[138:141], v[194:197], v[120:123]
	v_mfma_f32_16x16x32_f16 v[116:119], v[130:133], v[202:205], v[116:119]
	v_mfma_f32_16x16x32_f16 v[112:115], v[138:141], v[202:205], v[112:115]
	v_mfma_f32_16x16x32_f16 v[108:111], v[130:133], v[210:213], v[108:111]
	v_mfma_f32_16x16x32_f16 v[104:107], v[138:141], v[210:213], v[104:107]
	v_mfma_f32_16x16x32_f16 v[100:103], v[130:133], v[218:221], v[100:103]
	v_mfma_f32_16x16x32_f16 v[96:99], v[138:141], v[218:221], v[96:99]
	v_mfma_f32_16x16x32_f16 v[124:127], v[134:137], v[198:201], v[124:127]
	v_mfma_f32_16x16x32_f16 v[120:123], v[162:165], v[198:201], v[120:123]
	v_mfma_f32_16x16x32_f16 v[116:119], v[134:137], v[206:209], v[116:119]
	v_mfma_f32_16x16x32_f16 v[112:115], v[162:165], v[206:209], v[112:115]
	v_mfma_f32_16x16x32_f16 v[108:111], v[134:137], v[214:217], v[108:111]
	v_mfma_f32_16x16x32_f16 v[104:107], v[162:165], v[214:217], v[104:107]
	v_mfma_f32_16x16x32_f16 v[100:103], v[134:137], v[222:225], v[100:103]
	v_mfma_f32_16x16x32_f16 v[96:99], v[162:165], v[222:225], v[96:99]
	v_mfma_f32_16x16x32_f16 v[60:63], v[166:169], v[194:197], v[60:63]
	v_mfma_f32_16x16x32_f16 v[56:59], v[186:189], v[194:197], v[56:59]
	v_mfma_f32_16x16x32_f16 v[52:55], v[166:169], v[202:205], v[52:55]
	v_mfma_f32_16x16x32_f16 v[48:51], v[186:189], v[202:205], v[48:51]
	v_mfma_f32_16x16x32_f16 v[44:47], v[166:169], v[210:213], v[44:47]
	v_mfma_f32_16x16x32_f16 v[40:43], v[186:189], v[210:213], v[40:43]
	v_mfma_f32_16x16x32_f16 v[36:39], v[166:169], v[218:221], v[36:39]
	v_mfma_f32_16x16x32_f16 v[32:35], v[186:189], v[218:221], v[32:35]
	v_mfma_f32_16x16x32_f16 v[60:63], v[170:173], v[198:201], v[60:63]
	v_mfma_f32_16x16x32_f16 v[56:59], v[190:193], v[198:201], v[56:59]
	v_mfma_f32_16x16x32_f16 v[52:55], v[170:173], v[206:209], v[52:55]
	v_mfma_f32_16x16x32_f16 v[48:51], v[190:193], v[206:209], v[48:51]
	v_mfma_f32_16x16x32_f16 v[44:47], v[170:173], v[214:217], v[44:47]
	v_mfma_f32_16x16x32_f16 v[40:43], v[190:193], v[214:217], v[40:43]
	v_mfma_f32_16x16x32_f16 v[36:39], v[170:173], v[222:225], v[36:39]
	v_mfma_f32_16x16x32_f16 v[32:35], v[190:193], v[222:225], v[32:35]
	s_setprio 0
	s_barrier
	s_add_i32 s54, s68, s20
	s_mov_b32 m0, s54
	ds_read_b128 v[194:197], v240 offset:49152
	ds_read_b128 v[198:201], v240 offset:50176
	ds_read_b128 v[202:205], v240 offset:51200
	ds_read_b128 v[206:209], v240 offset:52224
	ds_read_b128 v[210:213], v240 offset:53248
	ds_read_b128 v[214:217], v240 offset:54272
	ds_read_b128 v[218:221], v240 offset:55296
	ds_read_b128 v[222:225], v240 offset:56320
	global_load_lds_dwordx4 v146, s[98:99]
	s_add_i32 m0, s54, 0x2000
	s_add_u32 s42, s42, 0x40080
	s_addc_u32 s43, s43, 0
	s_add_i32 s54, s69, s20
	global_load_lds_dwordx4 v142, s[98:99]
	s_mov_b32 m0, s54
	s_nop 0
	global_load_lds_dwordx4 v146, s[42:43]
	s_add_i32 m0, s54, 0x2000
	s_nop 0
	global_load_lds_dwordx4 v142, s[42:43]
	s_mov_b32 m0, s44
	s_nop 0
	global_load_lds_dwordx4 v148, s[100:101]
	s_mov_b32 m0, s45
	s_nop 0
	global_load_lds_dwordx4 v144, s[100:101]
	s_waitcnt vmcnt(8) lgkmcnt(0)
	s_barrier
	s_setprio 1
	v_mfma_f32_16x16x32_f16 v[92:95], v[130:133], v[194:197], v[92:95]
	v_mfma_f32_16x16x32_f16 v[88:91], v[138:141], v[194:197], v[88:91]
	v_mfma_f32_16x16x32_f16 v[84:87], v[130:133], v[202:205], v[84:87]
	v_mfma_f32_16x16x32_f16 v[80:83], v[138:141], v[202:205], v[80:83]
	v_mfma_f32_16x16x32_f16 v[76:79], v[130:133], v[210:213], v[76:79]
	v_mfma_f32_16x16x32_f16 v[72:75], v[138:141], v[210:213], v[72:75]
	v_mfma_f32_16x16x32_f16 v[68:71], v[130:133], v[218:221], v[68:71]
	v_mfma_f32_16x16x32_f16 v[64:67], v[138:141], v[218:221], v[64:67]
	v_mfma_f32_16x16x32_f16 v[92:95], v[134:137], v[198:201], v[92:95]
	v_mfma_f32_16x16x32_f16 v[88:91], v[162:165], v[198:201], v[88:91]
	v_mfma_f32_16x16x32_f16 v[84:87], v[134:137], v[206:209], v[84:87]
	v_mfma_f32_16x16x32_f16 v[80:83], v[162:165], v[206:209], v[80:83]
	v_mfma_f32_16x16x32_f16 v[76:79], v[134:137], v[214:217], v[76:79]
	v_mfma_f32_16x16x32_f16 v[72:75], v[162:165], v[214:217], v[72:75]
	v_mfma_f32_16x16x32_f16 v[68:71], v[134:137], v[222:225], v[68:71]
	v_mfma_f32_16x16x32_f16 v[64:67], v[162:165], v[222:225], v[64:67]
	v_mfma_f32_16x16x32_f16 v[28:31], v[166:169], v[194:197], v[28:31]
	v_mfma_f32_16x16x32_f16 v[24:27], v[186:189], v[194:197], v[24:27]
	v_mfma_f32_16x16x32_f16 v[20:23], v[166:169], v[202:205], v[20:23]
	v_mfma_f32_16x16x32_f16 v[16:19], v[186:189], v[202:205], v[16:19]
	v_mfma_f32_16x16x32_f16 v[12:15], v[166:169], v[210:213], v[12:15]
	v_mfma_f32_16x16x32_f16 v[8:11], v[186:189], v[210:213], v[8:11]
	v_mfma_f32_16x16x32_f16 v[4:7], v[166:169], v[218:221], v[4:7]
	v_mfma_f32_16x16x32_f16 v[0:3], v[186:189], v[218:221], v[0:3]
	v_mfma_f32_16x16x32_f16 v[28:31], v[170:173], v[198:201], v[28:31]
	v_mfma_f32_16x16x32_f16 v[24:27], v[190:193], v[198:201], v[24:27]
	v_mfma_f32_16x16x32_f16 v[20:23], v[170:173], v[206:209], v[20:23]
	v_mfma_f32_16x16x32_f16 v[16:19], v[190:193], v[206:209], v[16:19]
	v_mfma_f32_16x16x32_f16 v[12:15], v[170:173], v[214:217], v[12:15]
	v_mfma_f32_16x16x32_f16 v[8:11], v[190:193], v[214:217], v[8:11]
	v_mfma_f32_16x16x32_f16 v[4:7], v[170:173], v[222:225], v[4:7]
	v_mfma_f32_16x16x32_f16 v[0:3], v[190:193], v[222:225], v[0:3]
	s_setprio 0
	s_barrier
	s_add_i32 s67, s67, 2
	s_add_u32 s0, s0, 0x100
	s_addc_u32 s1, s1, 0
	s_add_u32 s59, s59, 0x100
	s_addc_u32 s61, s61, 0
	s_cmp_gt_u32 s67, 13
	s_cbranch_scc0 .LBB0_256
	s_and_b64 vcc, exec, s[8:9]
	s_cbranch_vccz .LBB0_259
	s_barrier

; #define PG8_STAGE(bufoff, gbase, voff) do { _Pragma("unroll") for (int _i = 0; _i < 2; ++_i) \
;         __builtin_amdgcn_global_load_lds((const unsigned*)((const char*)(gbase) + (voff)[_i]), (PG8_LAS unsigned*)(lds + (bufoff) + ldsw + _i * 8192), 16, 0, 0); } while (0)
; #define PG8_LDA(dst, b, h) do { _Pragma("unroll") for (int m = 0; m < 4; ++m) _Pragma("unroll") for (int k = 0; k < 2; ++k) dst[m][k] = *(const PG8_LAS bf16x8*)(lds + PG8_SA(b, h) + aoff + m * 2048 + k * 1024); } while (0)
; #define PG8_LDB(dst, b, h) do { _Pragma("unroll") for (int n = 0; n < 2; ++n) _Pragma("unroll") for (int k = 0; k < 2; ++k) dst[n][k] = *(const PG8_LAS bf16x8*)(lds + PG8_SB(b, h) + boff + n * 2048 + k * 1024); } while (0)
; #define PG8_MMA(ai, bj, At, Bt) do { __builtin_amdgcn_s_setprio(1); _Pragma("unroll") for (int m = 0; m < 4; ++m) _Pragma("unroll") for (int n = 0; n < 2; ++n) _Pragma("unroll") for (int k = 0; k < 2; ++k) \
;         acc[ai][bj][m][n] = mma16<F16>(Bt[n][k], At[m][k], acc[ai][bj][m][n]); __builtin_amdgcn_s_setprio(0); } while (0)
; #define PG8_WAIT_V(n) asm volatile("s_waitcnt vmcnt(" #n ")" ::: "memory")
; #define PG8_WAIT_L(n) asm volatile("s_waitcnt lgkmcnt(" #n ")" ::: "memory")
; #define PG8_BAR __builtin_amdgcn_s_barrier()
; #define PG8_SCHED __builtin_amdgcn_sched_barrier(0)
; template <class Epi, class Sched, bool ALIGN_EPI = false, bool SP2 = false, bool F16 = false>
; __device__ __forceinline__ void gemm_phase(PG8_LAS unsigned char* lds, const Gemm g, const Sched& S, const Epi& E) {
;     ...
;             const char* a1 = cA + (size_t)(t + 1) * kstep;
;             const char* a2 = last ? nA : cA + (size_t)(t + 2) * kstep; const char* b2 = last ? nB : cB + (size_t)(t + 2) * kstep;
;             const char* a3 = a2 + kstep; const char* b3 = b2 + kstep;
;             if (last && has_next) S.a_ready(nxt);
;             if constexpr (SP2) {
;             PG8_LDB(B0, 0, 0); PG8_LDB(B1, 0, 1); PG8_SCHED; PG8_LDA(At, 0, 0); PG8_STAGE(PG8_SA(1, 1), a1 + hstep, voffA);
;             PG8_WAIT_V(8); PG8_WAIT_L(0); PG8_BAR; PG8_MMA(0, 0, At, B0); PG8_MMA(0, 1, At, B1); PG8_BAR; PG8_SCHED;
;             PG8_LDA(At, 0, 1); PG8_STAGE(PG8_SB(0, 0), b2, voffB); PG8_STAGE(PG8_SB(0, 1), b2 + hstep, voffB); PG8_STAGE(PG8_SA(0, 0), a2, voffA);
;             PG8_WAIT_V(8); PG8_WAIT_L(0); PG8_BAR; PG8_MMA(1, 0, At, B0); PG8_MMA(1, 1, At, B1); PG8_BAR; PG8_SCHED;
.LBB0_801:
	s_add_u32 s0, s60, s62
	s_addc_u32 s1, s61, s63
	s_add_u32 s0, s0, 0x100
	s_addc_u32 s1, s1, 0
	s_add_u32 s4, s74, s62
	s_addc_u32 s5, s75, s63
	s_add_i32 s6, 0, 0x10000
	s_cmpk_eq_i32 s62, 0x700
	s_cselect_b32 s65, s55, s1
	s_cselect_b32 s64, s70, s0
	v_add_u32_e32 v128, s6, v239
	s_cselect_b32 s1, s53, s5
	s_cselect_b32 s0, s71, s4
	s_add_i32 s7, 0, 0x14000
	ds_read_b128 v[136:139], v128
	ds_read_b128 v[140:143], v128 offset:1024
	ds_read_b128 v[144:147], v128 offset:2048
	ds_read_b128 v[148:151], v128 offset:3072
	v_add_u32_e32 v128, s7, v239
	ds_read_b128 v[152:155], v128
	ds_read_b128 v[156:159], v128 offset:1024
	ds_read_b128 v[190:193], v128 offset:2048
	ds_read_b128 v[194:197], v128 offset:3072
	v_lshl_add_u64 v[130:131], v[132:133], 0, s[62:63]
	s_add_i32 m0, s11, 0xc000
	ds_read_b128 v[198:201], v240
	ds_read_b128 v[202:205], v240 offset:1024
	ds_read_b128 v[206:209], v240 offset:2048
	ds_read_b128 v[210:213], v240 offset:3072
	ds_read_b128 v[214:217], v240 offset:4096
	ds_read_b128 v[218:221], v240 offset:5120
	ds_read_b128 v[222:225], v240 offset:6144
	ds_read_b128 v[242:245], v240 offset:7168
	global_load_lds_dwordx4 v[130:131], off
	v_lshl_add_u64 v[130:131], v[134:135], 0, s[62:63]
	s_add_i32 m0, s11, 0xe000
	s_nop 0
	global_load_lds_dwordx4 v[130:131], off
	s_waitcnt vmcnt(8) lgkmcnt(0)
	s_barrier
	s_setprio 1
	v_mfma_f32_16x16x32_bf16 v[124:127], v[136:139], v[198:201], v[124:127]
	v_mfma_f32_16x16x32_bf16 v[120:123], v[144:147], v[198:201], v[120:123]
	v_mfma_f32_16x16x32_bf16 v[116:119], v[136:139], v[206:209], v[116:119]
	v_mfma_f32_16x16x32_bf16 v[112:115], v[144:147], v[206:209], v[112:115]
	v_mfma_f32_16x16x32_bf16 v[108:111], v[136:139], v[214:217], v[108:111]
	v_mfma_f32_16x16x32_bf16 v[104:107], v[144:147], v[214:217], v[104:107]
	v_mfma_f32_16x16x32_bf16 v[100:103], v[136:139], v[222:225], v[100:103]
	v_mfma_f32_16x16x32_bf16 v[96:99], v[144:147], v[222:225], v[96:99]
	v_mfma_f32_16x16x32_bf16 v[124:127], v[140:143], v[202:205], v[124:127]
	v_mfma_f32_16x16x32_bf16 v[120:123], v[148:151], v[202:205], v[120:123]
	v_mfma_f32_16x16x32_bf16 v[116:119], v[140:143], v[210:213], v[116:119]
	v_mfma_f32_16x16x32_bf16 v[112:115], v[148:151], v[210:213], v[112:115]
	v_mfma_f32_16x16x32_bf16 v[108:111], v[140:143], v[218:221], v[108:111]
	v_mfma_f32_16x16x32_bf16 v[104:107], v[148:151], v[218:221], v[104:107]
	v_mfma_f32_16x16x32_bf16 v[100:103], v[140:143], v[242:245], v[100:103]
	v_mfma_f32_16x16x32_bf16 v[96:99], v[148:151], v[242:245], v[96:99]
	v_mfma_f32_16x16x32_bf16 v[60:63], v[152:155], v[198:201], v[60:63]
	v_mfma_f32_16x16x32_bf16 v[56:59], v[190:193], v[198:201], v[56:59]
	v_mfma_f32_16x16x32_bf16 v[52:55], v[152:155], v[206:209], v[52:55]
	v_mfma_f32_16x16x32_bf16 v[48:51], v[190:193], v[206:209], v[48:51]
	v_mfma_f32_16x16x32_bf16 v[44:47], v[152:155], v[214:217], v[44:47]
	v_mfma_f32_16x16x32_bf16 v[40:43], v[190:193], v[214:217], v[40:43]
	v_mfma_f32_16x16x32_bf16 v[36:39], v[152:155], v[222:225], v[36:39]
	v_mfma_f32_16x16x32_bf16 v[32:35], v[190:193], v[222:225], v[32:35]
	v_mfma_f32_16x16x32_bf16 v[60:63], v[156:159], v[202:205], v[60:63]
	v_mfma_f32_16x16x32_bf16 v[56:59], v[194:197], v[202:205], v[56:59]
	v_mfma_f32_16x16x32_bf16 v[52:55], v[156:159], v[210:213], v[52:55]
	v_mfma_f32_16x16x32_bf16 v[48:51], v[194:197], v[210:213], v[48:51]
	v_mfma_f32_16x16x32_bf16 v[44:47], v[156:159], v[218:221], v[44:47]
	v_mfma_f32_16x16x32_bf16 v[40:43], v[194:197], v[218:221], v[40:43]
	v_mfma_f32_16x16x32_bf16 v[36:39], v[156:159], v[242:245], v[36:39]
	v_mfma_f32_16x16x32_bf16 v[32:35], v[194:197], v[242:245], v[32:35]
	s_setprio 0
	s_barrier
	s_add_i32 s4, s6, s10
	v_lshl_add_u64 v[130:131], s[0:1], 0, v[166:167]
	s_mov_b32 m0, s4
	ds_read_b128 v[198:201], v240 offset:16384
	ds_read_b128 v[202:205], v240 offset:17408
	ds_read_b128 v[206:209], v240 offset:18432
	ds_read_b128 v[210:213], v240 offset:19456
	ds_read_b128 v[214:217], v240 offset:20480
	ds_read_b128 v[218:221], v240 offset:21504
	ds_read_b128 v[222:225], v240 offset:22528
	ds_read_b128 v[242:245], v240 offset:23552
	global_load_lds_dwordx4 v[130:131], off
	s_add_i32 m0, s4, 0x2000
	s_add_u32 s4, s0, 0x40000
	v_lshl_add_u64 v[160:161], s[0:1], 0, v[162:163]
	s_addc_u32 s5, s1, 0
	s_add_i32 s6, s7, s10
	global_load_lds_dwordx4 v[160:161], off
	v_lshl_add_u64 v[246:247], s[4:5], 0, v[166:167]
	s_mov_b32 m0, s6
	v_lshl_add_u64 v[248:249], s[64:65], 0, v[164:165]
	global_load_lds_dwordx4 v[246:247], off
	v_lshl_add_u64 v[246:247], s[4:5], 0, v[162:163]
	s_add_i32 m0, s6, 0x2000
	s_nop 0
	global_load_lds_dwordx4 v[246:247], off
	v_lshl_add_u64 v[246:247], s[64:65], 0, v[168:169]
	s_mov_b32 m0, s11
	s_nop 0
	global_load_lds_dwordx4 v[246:247], off
	s_mov_b32 m0, s13
	s_nop 0
	global_load_lds_dwordx4 v[248:249], off
	s_waitcnt vmcnt(8) lgkmcnt(0)
	s_barrier
; #define PG8_STAGE(bufoff, gbase, voff) do { _Pragma("unroll") for (int _i = 0; _i < 2; ++_i) \
;         __builtin_amdgcn_global_load_lds((const unsigned*)((const char*)(gbase) + (voff)[_i]), (PG8_LAS unsigned*)(lds + (bufoff) + ldsw + _i * 8192), 16, 0, 0); } while (0)
; #define PG8_LDA(dst, b, h) do { _Pragma("unroll") for (int m = 0; m < 4; ++m) _Pragma("unroll") for (int k = 0; k < 2; ++k) dst[m][k] = *(const PG8_LAS bf16x8*)(lds + PG8_SA(b, h) + aoff + m * 2048 + k * 1024); } while (0)
; #define PG8_LDB(dst, b, h) do { _Pragma("unroll") for (int n = 0; n < 2; ++n) _Pragma("unroll") for (int k = 0; k < 2; ++k) dst[n][k] = *(const PG8_LAS bf16x8*)(lds + PG8_SB(b, h) + boff + n * 2048 + k * 1024); } while (0)
; #define PG8_MMA(ai, bj, At, Bt) do { __builtin_amdgcn_s_setprio(1); _Pragma("unroll") for (int m = 0; m < 4; ++m) _Pragma("unroll") for (int n = 0; n < 2; ++n) _Pragma("unroll") for (int k = 0; k < 2; ++k) \
;         acc[ai][bj][m][n] = mma16<F16>(Bt[n][k], At[m][k], acc[ai][bj][m][n]); __builtin_amdgcn_s_setprio(0); } while (0)
; #define PG8_WAIT_V(n) asm volatile("s_waitcnt vmcnt(" #n ")" ::: "memory")
; #define PG8_WAIT_L(n) asm volatile("s_waitcnt lgkmcnt(" #n ")" ::: "memory")
; #define PG8_BAR __builtin_amdgcn_s_barrier()
; #define PG8_SCHED __builtin_amdgcn_sched_barrier(0)
; template <class Epi, class Sched, bool ALIGN_EPI = false, bool SP2 = false, bool F16 = false>
; __device__ __forceinline__ void gemm_phase(PG8_LAS unsigned char* lds, const Gemm g, const Sched& S, const Epi& E) {
;     ...
;             PG8_WAIT_V(8); PG8_WAIT_L(0); PG8_BAR; PG8_MMA(1, 0, At, B0); PG8_MMA(1, 1, At, B1); PG8_BAR; PG8_SCHED;
;             PG8_LDB(B0, 1, 0); PG8_LDB(B1, 1, 1); PG8_SCHED; PG8_LDA(At, 1, 0); PG8_STAGE(PG8_SA(0, 1), a2 + hstep, voffA);
;             PG8_WAIT_V(8); PG8_WAIT_L(0); PG8_BAR; PG8_MMA(0, 0, At, B0); PG8_MMA(0, 1, At, B1); PG8_BAR; PG8_SCHED;
;             PG8_LDA(At, 1, 1); PG8_STAGE(PG8_SB(1, 0), b3, voffB); PG8_STAGE(PG8_SB(1, 1), b3 + hstep, voffB); PG8_STAGE(PG8_SA(1, 0), a3, voffA);
	s_setprio 1
	v_mfma_f32_16x16x32_bf16 v[92:95], v[136:139], v[198:201], v[92:95]
	v_mfma_f32_16x16x32_bf16 v[88:91], v[144:147], v[198:201], v[88:91]
	v_mfma_f32_16x16x32_bf16 v[84:87], v[136:139], v[206:209], v[84:87]
	v_mfma_f32_16x16x32_bf16 v[80:83], v[144:147], v[206:209], v[80:83]
	v_mfma_f32_16x16x32_bf16 v[76:79], v[136:139], v[214:217], v[76:79]
	v_mfma_f32_16x16x32_bf16 v[72:75], v[144:147], v[214:217], v[72:75]
	v_mfma_f32_16x16x32_bf16 v[68:71], v[136:139], v[222:225], v[68:71]
	v_mfma_f32_16x16x32_bf16 v[64:67], v[144:147], v[222:225], v[64:67]
	v_mfma_f32_16x16x32_bf16 v[92:95], v[140:143], v[202:205], v[92:95]
	v_mfma_f32_16x16x32_bf16 v[88:91], v[148:151], v[202:205], v[88:91]
	v_mfma_f32_16x16x32_bf16 v[84:87], v[140:143], v[210:213], v[84:87]
	v_mfma_f32_16x16x32_bf16 v[80:83], v[148:151], v[210:213], v[80:83]
	v_mfma_f32_16x16x32_bf16 v[76:79], v[140:143], v[218:221], v[76:79]
	v_mfma_f32_16x16x32_bf16 v[72:75], v[148:151], v[218:221], v[72:75]
	v_mfma_f32_16x16x32_bf16 v[68:71], v[140:143], v[242:245], v[68:71]
	v_mfma_f32_16x16x32_bf16 v[64:67], v[148:151], v[242:245], v[64:67]
	v_mfma_f32_16x16x32_bf16 v[28:31], v[152:155], v[198:201], v[28:31]
	v_mfma_f32_16x16x32_bf16 v[24:27], v[190:193], v[198:201], v[24:27]
	v_mfma_f32_16x16x32_bf16 v[20:23], v[152:155], v[206:209], v[20:23]
	v_mfma_f32_16x16x32_bf16 v[16:19], v[190:193], v[206:209], v[16:19]
	v_mfma_f32_16x16x32_bf16 v[12:15], v[152:155], v[214:217], v[12:15]
	v_mfma_f32_16x16x32_bf16 v[8:11], v[190:193], v[214:217], v[8:11]
	v_mfma_f32_16x16x32_bf16 v[4:7], v[152:155], v[222:225], v[4:7]
	v_mfma_f32_16x16x32_bf16 v[0:3], v[190:193], v[222:225], v[0:3]
	v_mfma_f32_16x16x32_bf16 v[28:31], v[156:159], v[202:205], v[28:31]
	v_mfma_f32_16x16x32_bf16 v[24:27], v[194:197], v[202:205], v[24:27]
	v_mfma_f32_16x16x32_bf16 v[20:23], v[156:159], v[210:213], v[20:23]
	v_mfma_f32_16x16x32_bf16 v[16:19], v[194:197], v[210:213], v[16:19]
	v_mfma_f32_16x16x32_bf16 v[12:15], v[156:159], v[218:221], v[12:15]
	v_mfma_f32_16x16x32_bf16 v[8:11], v[194:197], v[218:221], v[8:11]
	v_mfma_f32_16x16x32_bf16 v[4:7], v[156:159], v[242:245], v[4:7]
	v_mfma_f32_16x16x32_bf16 v[0:3], v[194:197], v[242:245], v[0:3]
	s_setprio 0
	s_barrier
	s_add_i32 s6, 0, 0x18000
	v_add_u32_e32 v128, s6, v239
	s_add_i32 s7, 0, 0x1c000
	ds_read_b128 v[136:139], v128
	ds_read_b128 v[140:143], v128 offset:1024
	ds_read_b128 v[144:147], v128 offset:2048
	ds_read_b128 v[148:151], v128 offset:3072
	v_add_u32_e32 v128, s7, v239
	ds_read_b128 v[152:155], v128
	ds_read_b128 v[156:159], v128 offset:1024
	ds_read_b128 v[190:193], v128 offset:2048
	ds_read_b128 v[194:197], v128 offset:3072
	s_add_u32 s4, s64, 0x40000
	s_addc_u32 s5, s65, 0
	s_mov_b32 m0, s14
	v_lshl_add_u64 v[250:251], s[4:5], 0, v[168:169]
	ds_read_b128 v[198:201], v240 offset:32768
	ds_read_b128 v[202:205], v240 offset:33792
	ds_read_b128 v[206:209], v240 offset:34816
	ds_read_b128 v[210:213], v240 offset:35840
	ds_read_b128 v[214:217], v240 offset:36864
	ds_read_b128 v[218:221], v240 offset:37888
	ds_read_b128 v[222:225], v240 offset:38912
	ds_read_b128 v[242:245], v240 offset:39936
	global_load_lds_dwordx4 v[250:251], off
	v_lshl_add_u64 v[250:251], s[4:5], 0, v[164:165]
	s_mov_b32 m0, s15
	s_nop 0
	global_load_lds_dwordx4 v[250:251], off
	s_waitcnt vmcnt(8) lgkmcnt(0)
	s_barrier
	s_setprio 1
	v_mfma_f32_16x16x32_bf16 v[124:127], v[136:139], v[198:201], v[124:127]
	v_mfma_f32_16x16x32_bf16 v[120:123], v[144:147], v[198:201], v[120:123]
	v_mfma_f32_16x16x32_bf16 v[116:119], v[136:139], v[206:209], v[116:119]
	v_mfma_f32_16x16x32_bf16 v[112:115], v[144:147], v[206:209], v[112:115]
	v_mfma_f32_16x16x32_bf16 v[108:111], v[136:139], v[214:217], v[108:111]
	v_mfma_f32_16x16x32_bf16 v[104:107], v[144:147], v[214:217], v[104:107]
	v_mfma_f32_16x16x32_bf16 v[100:103], v[136:139], v[222:225], v[100:103]
	v_mfma_f32_16x16x32_bf16 v[96:99], v[144:147], v[222:225], v[96:99]
	v_mfma_f32_16x16x32_bf16 v[124:127], v[140:143], v[202:205], v[124:127]
	v_mfma_f32_16x16x32_bf16 v[120:123], v[148:151], v[202:205], v[120:123]
	v_mfma_f32_16x16x32_bf16 v[116:119], v[140:143], v[210:213], v[116:119]
	v_mfma_f32_16x16x32_bf16 v[112:115], v[148:151], v[210:213], v[112:115]
	v_mfma_f32_16x16x32_bf16 v[108:111], v[140:143], v[218:221], v[108:111]
	v_mfma_f32_16x16x32_bf16 v[104:107], v[148:151], v[218:221], v[104:107]
	v_mfma_f32_16x16x32_bf16 v[100:103], v[140:143], v[242:245], v[100:103]
	v_mfma_f32_16x16x32_bf16 v[96:99], v[148:151], v[242:245], v[96:99]
	v_mfma_f32_16x16x32_bf16 v[60:63], v[152:155], v[198:201], v[60:63]
	v_mfma_f32_16x16x32_bf16 v[56:59], v[190:193], v[198:201], v[56:59]
	v_mfma_f32_16x16x32_bf16 v[52:55], v[152:155], v[206:209], v[52:55]
	v_mfma_f32_16x16x32_bf16 v[48:51], v[190:193], v[206:209], v[48:51]
	v_mfma_f32_16x16x32_bf16 v[44:47], v[152:155], v[214:217], v[44:47]
	v_mfma_f32_16x16x32_bf16 v[40:43], v[190:193], v[214:217], v[40:43]
	v_mfma_f32_16x16x32_bf16 v[36:39], v[152:155], v[222:225], v[36:39]
	v_mfma_f32_16x16x32_bf16 v[32:35], v[190:193], v[222:225], v[32:35]
	v_mfma_f32_16x16x32_bf16 v[60:63], v[156:159], v[202:205], v[60:63]
	v_mfma_f32_16x16x32_bf16 v[56:59], v[194:197], v[202:205], v[56:59]
	v_mfma_f32_16x16x32_bf16 v[52:55], v[156:159], v[210:213], v[52:55]
	v_mfma_f32_16x16x32_bf16 v[48:51], v[194:197], v[210:213], v[48:51]
	v_mfma_f32_16x16x32_bf16 v[44:47], v[156:159], v[218:221], v[44:47]
	v_mfma_f32_16x16x32_bf16 v[40:43], v[194:197], v[218:221], v[40:43]
	v_mfma_f32_16x16x32_bf16 v[36:39], v[156:159], v[242:245], v[36:39]
	v_mfma_f32_16x16x32_bf16 v[32:35], v[194:197], v[242:245], v[32:35]
	s_setprio 0
	s_barrier
; #define PG8_STAGE(bufoff, gbase, voff) do { _Pragma("unroll") for (int _i = 0; _i < 2; ++_i) \
;         __builtin_amdgcn_global_load_lds((const unsigned*)((const char*)(gbase) + (voff)[_i]), (PG8_LAS unsigned*)(lds + (bufoff) + ldsw + _i * 8192), 16, 0, 0); } while (0)
; #define PG8_LDA(dst, b, h) do { _Pragma("unroll") for (int m = 0; m < 4; ++m) _Pragma("unroll") for (int k = 0; k < 2; ++k) dst[m][k] = *(const PG8_LAS bf16x8*)(lds + PG8_SA(b, h) + aoff + m * 2048 + k * 1024); } while (0)
; #define PG8_MMA(ai, bj, At, Bt) do { __builtin_amdgcn_s_setprio(1); _Pragma("unroll") for (int m = 0; m < 4; ++m) _Pragma("unroll") for (int n = 0; n < 2; ++n) _Pragma("unroll") for (int k = 0; k < 2; ++k) \
;         acc[ai][bj][m][n] = mma16<F16>(Bt[n][k], At[m][k], acc[ai][bj][m][n]); __builtin_amdgcn_s_setprio(0); } while (0)
; #define PG8_WAIT_V(n) asm volatile("s_waitcnt vmcnt(" #n ")" ::: "memory")
; #define PG8_WAIT_L(n) asm volatile("s_waitcnt lgkmcnt(" #n ")" ::: "memory")
; #define PG8_BAR __builtin_amdgcn_s_barrier()
; #define PG8_SCHED __builtin_amdgcn_sched_barrier(0)
; template <class Epi, class Sched, bool ALIGN_EPI = false, bool SP2 = false, bool F16 = false>
; __device__ __forceinline__ void gemm_phase(PG8_LAS unsigned char* lds, const Gemm g, const Sched& S, const Epi& E) {
;     ...
;         for (int t = 0; t < nt; t += 2) {
;             if constexpr (Epi::KHOOK) { if (t == 4 || t == 10) E.khook(acc, cur, t, wr, fr); }
;     ...
;             PG8_LDA(At, 1, 1); PG8_STAGE(PG8_SB(1, 0), b3, voffB); PG8_STAGE(PG8_SB(1, 1), b3 + hstep, voffB); PG8_STAGE(PG8_SA(1, 0), a3, voffA);
;             PG8_WAIT_V(8); PG8_WAIT_L(0); PG8_BAR; PG8_MMA(1, 0, At, B0); PG8_MMA(1, 1, At, B1); PG8_BAR; PG8_SCHED;
	s_add_i32 s4, s6, s10
	v_lshl_add_u64 v[130:131], v[130:131], 0, s[16:17]
	s_mov_b32 m0, s4
	ds_read_b128 v[198:201], v240 offset:49152
	ds_read_b128 v[202:205], v240 offset:50176
	ds_read_b128 v[206:209], v240 offset:51200
	ds_read_b128 v[210:213], v240 offset:52224
	ds_read_b128 v[214:217], v240 offset:53248
	ds_read_b128 v[218:221], v240 offset:54272
	ds_read_b128 v[222:225], v240 offset:55296
	ds_read_b128 v[242:245], v240 offset:56320
	global_load_lds_dwordx4 v[130:131], off
	s_add_i32 m0, s4, 0x2000
	s_add_u32 s0, s0, 0x40080
	v_lshl_add_u64 v[130:131], v[160:161], 0, s[16:17]
	s_addc_u32 s1, s1, 0
	s_add_i32 s4, s7, s10
	global_load_lds_dwordx4 v[130:131], off
	v_lshl_add_u64 v[130:131], s[0:1], 0, v[166:167]
	s_mov_b32 m0, s4
	s_nop 0
	global_load_lds_dwordx4 v[130:131], off
	v_lshl_add_u64 v[130:131], s[0:1], 0, v[162:163]
	s_add_i32 m0, s4, 0x2000
	s_nop 0
	global_load_lds_dwordx4 v[130:131], off
	v_lshl_add_u64 v[130:131], v[246:247], 0, s[16:17]
	s_mov_b32 m0, s30
	s_nop 0
	global_load_lds_dwordx4 v[130:131], off
	v_lshl_add_u64 v[130:131], v[248:249], 0, s[16:17]
	s_mov_b32 m0, s31
	s_nop 0
	global_load_lds_dwordx4 v[130:131], off
	s_waitcnt vmcnt(8) lgkmcnt(0)
	s_barrier
	s_setprio 1
	v_mfma_f32_16x16x32_bf16 v[92:95], v[136:139], v[198:201], v[92:95]
	v_mfma_f32_16x16x32_bf16 v[88:91], v[144:147], v[198:201], v[88:91]
	v_mfma_f32_16x16x32_bf16 v[84:87], v[136:139], v[206:209], v[84:87]
	v_mfma_f32_16x16x32_bf16 v[80:83], v[144:147], v[206:209], v[80:83]
	v_mfma_f32_16x16x32_bf16 v[76:79], v[136:139], v[214:217], v[76:79]
	v_mfma_f32_16x16x32_bf16 v[72:75], v[144:147], v[214:217], v[72:75]
	v_mfma_f32_16x16x32_bf16 v[68:71], v[136:139], v[222:225], v[68:71]
	v_mfma_f32_16x16x32_bf16 v[64:67], v[144:147], v[222:225], v[64:67]
	v_mfma_f32_16x16x32_bf16 v[92:95], v[140:143], v[202:205], v[92:95]
	v_mfma_f32_16x16x32_bf16 v[88:91], v[148:151], v[202:205], v[88:91]
	v_mfma_f32_16x16x32_bf16 v[84:87], v[140:143], v[210:213], v[84:87]
	v_mfma_f32_16x16x32_bf16 v[80:83], v[148:151], v[210:213], v[80:83]
	v_mfma_f32_16x16x32_bf16 v[76:79], v[140:143], v[218:221], v[76:79]
	v_mfma_f32_16x16x32_bf16 v[72:75], v[148:151], v[218:221], v[72:75]
	v_mfma_f32_16x16x32_bf16 v[68:71], v[140:143], v[242:245], v[68:71]
	v_mfma_f32_16x16x32_bf16 v[64:67], v[148:151], v[242:245], v[64:67]
	v_mfma_f32_16x16x32_bf16 v[28:31], v[152:155], v[198:201], v[28:31]
	v_mfma_f32_16x16x32_bf16 v[24:27], v[190:193], v[198:201], v[24:27]
	v_mfma_f32_16x16x32_bf16 v[20:23], v[152:155], v[206:209], v[20:23]
	v_mfma_f32_16x16x32_bf16 v[16:19], v[190:193], v[206:209], v[16:19]
	v_mfma_f32_16x16x32_bf16 v[12:15], v[152:155], v[214:217], v[12:15]
	v_mfma_f32_16x16x32_bf16 v[8:11], v[190:193], v[214:217], v[8:11]
	v_mfma_f32_16x16x32_bf16 v[4:7], v[152:155], v[222:225], v[4:7]
	v_mfma_f32_16x16x32_bf16 v[0:3], v[190:193], v[222:225], v[0:3]
	v_mfma_f32_16x16x32_bf16 v[28:31], v[156:159], v[202:205], v[28:31]
	v_mfma_f32_16x16x32_bf16 v[24:27], v[194:197], v[202:205], v[24:27]
	v_mfma_f32_16x16x32_bf16 v[20:23], v[156:159], v[210:213], v[20:23]
	v_mfma_f32_16x16x32_bf16 v[16:19], v[194:197], v[210:213], v[16:19]
	v_mfma_f32_16x16x32_bf16 v[12:15], v[156:159], v[218:221], v[12:15]
	v_mfma_f32_16x16x32_bf16 v[8:11], v[194:197], v[218:221], v[8:11]
	v_mfma_f32_16x16x32_bf16 v[4:7], v[156:159], v[242:245], v[4:7]
	v_mfma_f32_16x16x32_bf16 v[0:3], v[194:197], v[242:245], v[0:3]
	s_setprio 0
	s_barrier
	s_add_i32 s0, s78, 2
	s_add_u32 s62, s62, 0x100
	s_addc_u32 s63, s63, 0
	s_cmp_gt_u32 s78, 13
	s_cbranch_scc1 .LBB0_804
	s_mov_b32 s78, s0
	s_cmp_lt_i32 s78, 10
	s_cbranch_scc1 .LBB0_796
	s_branch .LBB0_795

; #define PG8_STAGE(bufoff, gbase, voff) do { _Pragma("unroll") for (int _i = 0; _i < 2; ++_i) \
;         __builtin_amdgcn_global_load_lds((const unsigned*)((const char*)(gbase) + (voff)[_i]), (PG8_LAS unsigned*)(lds + (bufoff) + ldsw + _i * 8192), 16, 0, 0); } while (0)
; #define PG8_LDA(dst, b, h) do { _Pragma("unroll") for (int m = 0; m < 4; ++m) _Pragma("unroll") for (int k = 0; k < 2; ++k) dst[m][k] = *(const PG8_LAS bf16x8*)(lds + PG8_SA(b, h) + aoff + m * 2048 + k * 1024); } while (0)
; #define PG8_LDB(dst, b, h) do { _Pragma("unroll") for (int n = 0; n < 2; ++n) _Pragma("unroll") for (int k = 0; k < 2; ++k) dst[n][k] = *(const PG8_LAS bf16x8*)(lds + PG8_SB(b, h) + boff + n * 2048 + k * 1024); } while (0)
; #define PG8_MMA(ai, bj, At, Bt) do { __builtin_amdgcn_s_setprio(1); _Pragma("unroll") for (int m = 0; m < 4; ++m) _Pragma("unroll") for (int n = 0; n < 2; ++n) _Pragma("unroll") for (int k = 0; k < 2; ++k) \
;         acc[ai][bj][m][n] = mma16<F16>(Bt[n][k], At[m][k], acc[ai][bj][m][n]); __builtin_amdgcn_s_setprio(0); } while (0)
; #define PG8_WAIT_V(n) asm volatile("s_waitcnt vmcnt(" #n ")" ::: "memory")
; #define PG8_WAIT_L(n) asm volatile("s_waitcnt lgkmcnt(" #n ")" ::: "memory")
; #define PG8_BAR __builtin_amdgcn_s_barrier()
; #define PG8_SCHED __builtin_amdgcn_sched_barrier(0)
; template <class Epi, class Sched, bool ALIGN_EPI = false, bool SP2 = false, bool F16 = false>
; __device__ __forceinline__ void gemm_phase(PG8_LAS unsigned char* lds, const Gemm g, const Sched& S, const Epi& E) {
;     ...
;             const char* a1 = cA + (size_t)(t + 1) * kstep;
;             const char* a2 = last ? nA : cA + (size_t)(t + 2) * kstep; const char* b2 = last ? nB : cB + (size_t)(t + 2) * kstep;
;             const char* a3 = a2 + kstep; const char* b3 = b2 + kstep;
;             if (last && has_next) S.a_ready(nxt);
;             if constexpr (SP2) {
;             PG8_LDB(B0, 0, 0); PG8_LDB(B1, 0, 1); PG8_SCHED; PG8_LDA(At, 0, 0); PG8_STAGE(PG8_SA(1, 1), a1 + hstep, voffA);
;             PG8_WAIT_V(8); PG8_WAIT_L(0); PG8_BAR; PG8_MMA(0, 0, At, B0); PG8_MMA(0, 1, At, B1); PG8_BAR; PG8_SCHED;
;             PG8_LDA(At, 0, 1); PG8_STAGE(PG8_SB(0, 0), b2, voffB); PG8_STAGE(PG8_SB(0, 1), b2 + hstep, voffB); PG8_STAGE(PG8_SA(0, 0), a2, voffA);
;             PG8_WAIT_V(8); PG8_WAIT_L(0); PG8_BAR; PG8_MMA(1, 0, At, B0); PG8_MMA(1, 1, At, B1); PG8_BAR; PG8_SCHED;
.LBB0_904:
	s_add_u32 s56, s54, 0xfffc0080
	s_addc_u32 s57, s55, -1
	s_add_i32 s62, 0, 0x10000
	s_cmp_eq_u32 s61, 12
	s_cselect_b32 s59, s4, s57
	s_cselect_b32 s58, s5, s56
	s_cselect_b32 s57, s37, s60
	s_cselect_b32 s56, s47, s49
	s_add_i32 s64, 0, 0x14000
	ds_read_b128 v[32:35], v172
	ds_read_b128 v[36:39], v172 offset:1024
	ds_read_b128 v[40:43], v172 offset:2048
	ds_read_b128 v[44:47], v172 offset:3072
	ds_read_b128 v[156:159], v172 offset:16384
	ds_read_b128 v[168:171], v172 offset:17408
	ds_read_b128 v[186:189], v172 offset:18432
	ds_read_b128 v[190:193], v172 offset:19456
	s_add_i32 m0, s9, 0xc000
	ds_read_b128 v[194:197], v165
	ds_read_b128 v[198:201], v165 offset:1024
	ds_read_b128 v[202:205], v165 offset:2048
	ds_read_b128 v[206:209], v165 offset:3072
	ds_read_b128 v[210:213], v165 offset:4096
	ds_read_b128 v[214:217], v165 offset:5120
	ds_read_b128 v[218:221], v165 offset:6144
	ds_read_b128 v[222:225], v165 offset:7168
	global_load_lds_dwordx4 v152, s[54:55]
	s_add_i32 m0, s9, 0xe000
	s_nop 0
	global_load_lds_dwordx4 v154, s[54:55]
	s_waitcnt vmcnt(8) lgkmcnt(0)
	s_barrier
	s_setprio 1
	v_mfma_f32_16x16x32_f16 v[142:145], v[32:35], v[194:197], v[142:145]
	v_mfma_f32_16x16x32_f16 v[138:141], v[40:43], v[194:197], v[138:141]
	v_mfma_f32_16x16x32_f16 v[124:127], v[32:35], v[202:205], v[124:127]
	v_mfma_f32_16x16x32_f16 v[120:123], v[40:43], v[202:205], v[120:123]
	v_mfma_f32_16x16x32_f16 v[108:111], v[32:35], v[210:213], v[108:111]
	v_mfma_f32_16x16x32_f16 v[104:107], v[40:43], v[210:213], v[104:107]
	v_mfma_f32_16x16x32_f16 v[92:95], v[32:35], v[218:221], v[92:95]
	v_mfma_f32_16x16x32_f16 v[88:91], v[40:43], v[218:221], v[88:91]
	v_mfma_f32_16x16x32_f16 v[142:145], v[36:39], v[198:201], v[142:145]
	v_mfma_f32_16x16x32_f16 v[138:141], v[44:47], v[198:201], v[138:141]
	v_mfma_f32_16x16x32_f16 v[124:127], v[36:39], v[206:209], v[124:127]
	v_mfma_f32_16x16x32_f16 v[120:123], v[44:47], v[206:209], v[120:123]
	v_mfma_f32_16x16x32_f16 v[108:111], v[36:39], v[214:217], v[108:111]
	v_mfma_f32_16x16x32_f16 v[104:107], v[44:47], v[214:217], v[104:107]
	v_mfma_f32_16x16x32_f16 v[92:95], v[36:39], v[222:225], v[92:95]
	v_mfma_f32_16x16x32_f16 v[88:91], v[44:47], v[222:225], v[88:91]
	v_mfma_f32_16x16x32_f16 v[134:137], v[156:159], v[194:197], v[134:137]
	v_mfma_f32_16x16x32_f16 v[130:133], v[186:189], v[194:197], v[130:133]
	v_mfma_f32_16x16x32_f16 v[116:119], v[156:159], v[202:205], v[116:119]
	v_mfma_f32_16x16x32_f16 v[112:115], v[186:189], v[202:205], v[112:115]
	v_mfma_f32_16x16x32_f16 v[100:103], v[156:159], v[210:213], v[100:103]
	v_mfma_f32_16x16x32_f16 v[96:99], v[186:189], v[210:213], v[96:99]
	v_mfma_f32_16x16x32_f16 v[84:87], v[156:159], v[218:221], v[84:87]
	v_mfma_f32_16x16x32_f16 v[80:83], v[186:189], v[218:221], v[80:83]
	v_mfma_f32_16x16x32_f16 v[134:137], v[168:171], v[198:201], v[134:137]
	v_mfma_f32_16x16x32_f16 v[130:133], v[190:193], v[198:201], v[130:133]
	v_mfma_f32_16x16x32_f16 v[116:119], v[168:171], v[206:209], v[116:119]
	v_mfma_f32_16x16x32_f16 v[112:115], v[190:193], v[206:209], v[112:115]
	v_mfma_f32_16x16x32_f16 v[100:103], v[168:171], v[214:217], v[100:103]
	v_mfma_f32_16x16x32_f16 v[96:99], v[190:193], v[214:217], v[96:99]
	v_mfma_f32_16x16x32_f16 v[84:87], v[168:171], v[222:225], v[84:87]
	v_mfma_f32_16x16x32_f16 v[80:83], v[190:193], v[222:225], v[80:83]
	s_setprio 0
	s_barrier
	s_add_u32 s98, s56, s16
	s_addc_u32 s99, s57, s17
	s_add_u32 s100, s58, s16
	s_addc_u32 s101, s59, s17
	s_add_i32 s62, s62, s8
	s_mov_b32 m0, s62
	ds_read_b128 v[194:197], v165 offset:16384
	ds_read_b128 v[198:201], v165 offset:17408
	ds_read_b128 v[202:205], v165 offset:18432
	ds_read_b128 v[206:209], v165 offset:19456
	ds_read_b128 v[210:213], v165 offset:20480
	ds_read_b128 v[214:217], v165 offset:21504
	ds_read_b128 v[218:221], v165 offset:22528
	ds_read_b128 v[222:225], v165 offset:23552
	global_load_lds_dwordx4 v128, s[56:57]
	s_add_i32 m0, s62, 0x2000
	s_add_u32 s62, s56, 0x40000
	s_addc_u32 s63, s57, 0
	s_add_i32 s64, s64, s8
	global_load_lds_dwordx4 v146, s[56:57]
	s_mov_b32 m0, s64
	s_nop 0
	global_load_lds_dwordx4 v128, s[62:63]
	s_add_i32 m0, s64, 0x2000
	s_nop 0
	global_load_lds_dwordx4 v146, s[62:63]
	s_mov_b32 m0, s9
	s_nop 0
	global_load_lds_dwordx4 v150, s[58:59]
	s_mov_b32 m0, s10
	s_nop 0
	global_load_lds_dwordx4 v148, s[58:59]
	s_waitcnt vmcnt(8) lgkmcnt(0)
	s_barrier
	s_setprio 1
	v_mfma_f32_16x16x32_f16 v[76:79], v[32:35], v[194:197], v[76:79]
	v_mfma_f32_16x16x32_f16 v[72:75], v[40:43], v[194:197], v[72:75]
	v_mfma_f32_16x16x32_f16 v[60:63], v[32:35], v[202:205], v[60:63]
	v_mfma_f32_16x16x32_f16 v[56:59], v[40:43], v[202:205], v[56:59]
	v_mfma_f32_16x16x32_f16 v[28:31], v[32:35], v[210:213], v[28:31]
	v_mfma_f32_16x16x32_f16 v[24:27], v[40:43], v[210:213], v[24:27]
	v_mfma_f32_16x16x32_f16 v[12:15], v[32:35], v[218:221], v[12:15]
	v_mfma_f32_16x16x32_f16 v[8:11], v[40:43], v[218:221], v[8:11]
	v_mfma_f32_16x16x32_f16 v[76:79], v[36:39], v[198:201], v[76:79]
	v_mfma_f32_16x16x32_f16 v[72:75], v[44:47], v[198:201], v[72:75]
	v_mfma_f32_16x16x32_f16 v[60:63], v[36:39], v[206:209], v[60:63]
	v_mfma_f32_16x16x32_f16 v[56:59], v[44:47], v[206:209], v[56:59]
	v_mfma_f32_16x16x32_f16 v[28:31], v[36:39], v[214:217], v[28:31]
	v_mfma_f32_16x16x32_f16 v[24:27], v[44:47], v[214:217], v[24:27]
	v_mfma_f32_16x16x32_f16 v[12:15], v[36:39], v[222:225], v[12:15]
	v_mfma_f32_16x16x32_f16 v[8:11], v[44:47], v[222:225], v[8:11]
	v_mfma_f32_16x16x32_f16 v[20:23], v[156:159], v[210:213], v[20:23]
	v_mfma_f32_16x16x32_f16 v[16:19], v[186:189], v[210:213], v[16:19]
	v_mfma_f32_16x16x32_f16 v[4:7], v[156:159], v[218:221], v[4:7]
	v_mfma_f32_16x16x32_f16 v[0:3], v[186:189], v[218:221], v[0:3]
	v_mfma_f32_16x16x32_f16 v[32:35], v[156:159], v[194:197], v[68:71]
	v_mfma_f32_16x16x32_f16 v[36:39], v[186:189], v[194:197], v[64:67]
	v_mfma_f32_16x16x32_f16 v[40:43], v[156:159], v[202:205], v[52:55]
	v_mfma_f32_16x16x32_f16 v[44:47], v[186:189], v[202:205], v[48:51]
	v_mfma_f32_16x16x32_f16 v[20:23], v[168:171], v[214:217], v[20:23]
	v_mfma_f32_16x16x32_f16 v[16:19], v[190:193], v[214:217], v[16:19]
	v_mfma_f32_16x16x32_f16 v[4:7], v[168:171], v[222:225], v[4:7]
	v_mfma_f32_16x16x32_f16 v[0:3], v[190:193], v[222:225], v[0:3]
	v_mfma_f32_16x16x32_f16 v[32:35], v[168:171], v[198:201], v[32:35]
	v_mfma_f32_16x16x32_f16 v[36:39], v[190:193], v[198:201], v[36:39]
	v_mfma_f32_16x16x32_f16 v[40:43], v[168:171], v[206:209], v[40:43]
	v_mfma_f32_16x16x32_f16 v[44:47], v[190:193], v[206:209], v[44:47]
	s_setprio 0
	s_barrier
; #define PG8_STAGE(bufoff, gbase, voff) do { _Pragma("unroll") for (int _i = 0; _i < 2; ++_i) \
;         __builtin_amdgcn_global_load_lds((const unsigned*)((const char*)(gbase) + (voff)[_i]), (PG8_LAS unsigned*)(lds + (bufoff) + ldsw + _i * 8192), 16, 0, 0); } while (0)
; #define PG8_LDA(dst, b, h) do { _Pragma("unroll") for (int m = 0; m < 4; ++m) _Pragma("unroll") for (int k = 0; k < 2; ++k) dst[m][k] = *(const PG8_LAS bf16x8*)(lds + PG8_SA(b, h) + aoff + m * 2048 + k * 1024); } while (0)
; #define PG8_LDB(dst, b, h) do { _Pragma("unroll") for (int n = 0; n < 2; ++n) _Pragma("unroll") for (int k = 0; k < 2; ++k) dst[n][k] = *(const PG8_LAS bf16x8*)(lds + PG8_SB(b, h) + boff + n * 2048 + k * 1024); } while (0)
; #define PG8_MMA(ai, bj, At, Bt) do { __builtin_amdgcn_s_setprio(1); _Pragma("unroll") for (int m = 0; m < 4; ++m) _Pragma("unroll") for (int n = 0; n < 2; ++n) _Pragma("unroll") for (int k = 0; k < 2; ++k) \
;         acc[ai][bj][m][n] = mma16<F16>(Bt[n][k], At[m][k], acc[ai][bj][m][n]); __builtin_amdgcn_s_setprio(0); } while (0)
; #define PG8_WAIT_V(n) asm volatile("s_waitcnt vmcnt(" #n ")" ::: "memory")
; #define PG8_WAIT_L(n) asm volatile("s_waitcnt lgkmcnt(" #n ")" ::: "memory")
; #define PG8_BAR __builtin_amdgcn_s_barrier()
; #define PG8_SCHED __builtin_amdgcn_sched_barrier(0)
; template <class Epi, class Sched, bool ALIGN_EPI = false, bool SP2 = false, bool F16 = false>
; __device__ __forceinline__ void gemm_phase(PG8_LAS unsigned char* lds, const Gemm g, const Sched& S, const Epi& E) {
;     ...
;             PG8_LDB(B0, 1, 0); PG8_LDB(B1, 1, 1); PG8_SCHED; PG8_LDA(At, 1, 0); PG8_STAGE(PG8_SA(0, 1), a2 + hstep, voffA);
;             PG8_WAIT_V(8); PG8_WAIT_L(0); PG8_BAR; PG8_MMA(0, 0, At, B0); PG8_MMA(0, 1, At, B1); PG8_BAR; PG8_SCHED;
;             PG8_LDA(At, 1, 1); PG8_STAGE(PG8_SB(1, 0), b3, voffB); PG8_STAGE(PG8_SB(1, 1), b3 + hstep, voffB); PG8_STAGE(PG8_SA(1, 0), a3, voffA);
;             PG8_WAIT_V(8); PG8_WAIT_L(0); PG8_BAR; PG8_MMA(1, 0, At, B0); PG8_MMA(1, 1, At, B1); PG8_BAR; PG8_SCHED;
	s_add_i32 s62, 0, 0x18000
	s_add_i32 s63, 0, 0x1c000
	ds_read_b128 v[48:51], v172 offset:32768
	ds_read_b128 v[52:55], v172 offset:33792
	ds_read_b128 v[64:67], v172 offset:34816
	ds_read_b128 v[68:71], v172 offset:35840
	ds_read_b128 v[156:159], v172 offset:49152
	ds_read_b128 v[168:171], v172 offset:50176
	ds_read_b128 v[186:189], v172 offset:51200
	ds_read_b128 v[190:193], v172 offset:52224
	s_add_u32 s58, s58, 0x40000
	s_addc_u32 s59, s59, 0
	s_mov_b32 m0, s11
	ds_read_b128 v[194:197], v165 offset:32768
	ds_read_b128 v[198:201], v165 offset:33792
	ds_read_b128 v[202:205], v165 offset:34816
	ds_read_b128 v[206:209], v165 offset:35840
	ds_read_b128 v[210:213], v165 offset:36864
	ds_read_b128 v[214:217], v165 offset:37888
	ds_read_b128 v[218:221], v165 offset:38912
	ds_read_b128 v[222:225], v165 offset:39936
	global_load_lds_dwordx4 v150, s[58:59]
	s_mov_b32 m0, s13
	s_nop 0
	global_load_lds_dwordx4 v148, s[58:59]
	s_waitcnt vmcnt(8) lgkmcnt(0)
	s_barrier
	s_setprio 1
	v_mfma_f32_16x16x32_f16 v[142:145], v[48:51], v[194:197], v[142:145]
	v_mfma_f32_16x16x32_f16 v[138:141], v[64:67], v[194:197], v[138:141]
	v_mfma_f32_16x16x32_f16 v[124:127], v[48:51], v[202:205], v[124:127]
	v_mfma_f32_16x16x32_f16 v[120:123], v[64:67], v[202:205], v[120:123]
	v_mfma_f32_16x16x32_f16 v[108:111], v[48:51], v[210:213], v[108:111]
	v_mfma_f32_16x16x32_f16 v[104:107], v[64:67], v[210:213], v[104:107]
	v_mfma_f32_16x16x32_f16 v[92:95], v[48:51], v[218:221], v[92:95]
	v_mfma_f32_16x16x32_f16 v[88:91], v[64:67], v[218:221], v[88:91]
	v_mfma_f32_16x16x32_f16 v[142:145], v[52:55], v[198:201], v[142:145]
	v_mfma_f32_16x16x32_f16 v[138:141], v[68:71], v[198:201], v[138:141]
	v_mfma_f32_16x16x32_f16 v[124:127], v[52:55], v[206:209], v[124:127]
	v_mfma_f32_16x16x32_f16 v[120:123], v[68:71], v[206:209], v[120:123]
	v_mfma_f32_16x16x32_f16 v[108:111], v[52:55], v[214:217], v[108:111]
	v_mfma_f32_16x16x32_f16 v[104:107], v[68:71], v[214:217], v[104:107]
	v_mfma_f32_16x16x32_f16 v[92:95], v[52:55], v[222:225], v[92:95]
	v_mfma_f32_16x16x32_f16 v[88:91], v[68:71], v[222:225], v[88:91]
	v_mfma_f32_16x16x32_f16 v[134:137], v[156:159], v[194:197], v[134:137]
	v_mfma_f32_16x16x32_f16 v[130:133], v[186:189], v[194:197], v[130:133]
	v_mfma_f32_16x16x32_f16 v[116:119], v[156:159], v[202:205], v[116:119]
	v_mfma_f32_16x16x32_f16 v[112:115], v[186:189], v[202:205], v[112:115]
	v_mfma_f32_16x16x32_f16 v[100:103], v[156:159], v[210:213], v[100:103]
	v_mfma_f32_16x16x32_f16 v[96:99], v[186:189], v[210:213], v[96:99]
	v_mfma_f32_16x16x32_f16 v[84:87], v[156:159], v[218:221], v[84:87]
	v_mfma_f32_16x16x32_f16 v[80:83], v[186:189], v[218:221], v[80:83]
	v_mfma_f32_16x16x32_f16 v[134:137], v[168:171], v[198:201], v[134:137]
	v_mfma_f32_16x16x32_f16 v[130:133], v[190:193], v[198:201], v[130:133]
	v_mfma_f32_16x16x32_f16 v[116:119], v[168:171], v[206:209], v[116:119]
	v_mfma_f32_16x16x32_f16 v[112:115], v[190:193], v[206:209], v[112:115]
	v_mfma_f32_16x16x32_f16 v[100:103], v[168:171], v[214:217], v[100:103]
	v_mfma_f32_16x16x32_f16 v[96:99], v[190:193], v[214:217], v[96:99]
	v_mfma_f32_16x16x32_f16 v[84:87], v[168:171], v[222:225], v[84:87]
	v_mfma_f32_16x16x32_f16 v[80:83], v[190:193], v[222:225], v[80:83]
	s_setprio 0
	s_barrier
	s_add_i32 s58, s62, s8
	s_mov_b32 m0, s58
	ds_read_b128 v[194:197], v165 offset:49152
	ds_read_b128 v[198:201], v165 offset:50176
	ds_read_b128 v[202:205], v165 offset:51200
	ds_read_b128 v[206:209], v165 offset:52224
	ds_read_b128 v[210:213], v165 offset:53248
	ds_read_b128 v[214:217], v165 offset:54272
	ds_read_b128 v[218:221], v165 offset:55296
	ds_read_b128 v[222:225], v165 offset:56320
	global_load_lds_dwordx4 v128, s[98:99]
	s_add_i32 m0, s58, 0x2000
	s_add_u32 s56, s56, 0x40080
	s_addc_u32 s57, s57, 0
	s_add_i32 s58, s63, s8
	global_load_lds_dwordx4 v146, s[98:99]
	s_mov_b32 m0, s58
	s_nop 0
	global_load_lds_dwordx4 v128, s[56:57]
	s_add_i32 m0, s58, 0x2000
	s_nop 0
	global_load_lds_dwordx4 v146, s[56:57]
	s_mov_b32 m0, s20
	s_nop 0
	global_load_lds_dwordx4 v150, s[100:101]
	s_mov_b32 m0, s21
	s_nop 0
	global_load_lds_dwordx4 v148, s[100:101]
	s_waitcnt vmcnt(8) lgkmcnt(0)
	s_barrier
	s_setprio 1
	v_mfma_f32_16x16x32_f16 v[76:79], v[48:51], v[194:197], v[76:79]
	v_mfma_f32_16x16x32_f16 v[72:75], v[64:67], v[194:197], v[72:75]
	v_mfma_f32_16x16x32_f16 v[60:63], v[48:51], v[202:205], v[60:63]
	v_mfma_f32_16x16x32_f16 v[56:59], v[64:67], v[202:205], v[56:59]
	v_mfma_f32_16x16x32_f16 v[28:31], v[48:51], v[210:213], v[28:31]
	v_mfma_f32_16x16x32_f16 v[24:27], v[64:67], v[210:213], v[24:27]
	v_mfma_f32_16x16x32_f16 v[12:15], v[48:51], v[218:221], v[12:15]
	v_mfma_f32_16x16x32_f16 v[8:11], v[64:67], v[218:221], v[8:11]
	v_mfma_f32_16x16x32_f16 v[76:79], v[52:55], v[198:201], v[76:79]
	v_mfma_f32_16x16x32_f16 v[72:75], v[68:71], v[198:201], v[72:75]
	v_mfma_f32_16x16x32_f16 v[60:63], v[52:55], v[206:209], v[60:63]
	v_mfma_f32_16x16x32_f16 v[56:59], v[68:71], v[206:209], v[56:59]
	v_mfma_f32_16x16x32_f16 v[28:31], v[52:55], v[214:217], v[28:31]
	v_mfma_f32_16x16x32_f16 v[24:27], v[68:71], v[214:217], v[24:27]
	v_mfma_f32_16x16x32_f16 v[12:15], v[52:55], v[222:225], v[12:15]
	v_mfma_f32_16x16x32_f16 v[8:11], v[68:71], v[222:225], v[8:11]
	v_mfma_f32_16x16x32_f16 v[32:35], v[156:159], v[194:197], v[32:35]
	v_mfma_f32_16x16x32_f16 v[68:71], v[168:171], v[198:201], v[32:35]
	v_mfma_f32_16x16x32_f16 v[32:35], v[186:189], v[194:197], v[36:39]
	v_mfma_f32_16x16x32_f16 v[64:67], v[190:193], v[198:201], v[32:35]
	v_mfma_f32_16x16x32_f16 v[32:35], v[156:159], v[202:205], v[40:43]
	v_mfma_f32_16x16x32_f16 v[52:55], v[168:171], v[206:209], v[32:35]
	v_mfma_f32_16x16x32_f16 v[32:35], v[186:189], v[202:205], v[44:47]
	v_mfma_f32_16x16x32_f16 v[20:23], v[156:159], v[210:213], v[20:23]
	v_mfma_f32_16x16x32_f16 v[16:19], v[186:189], v[210:213], v[16:19]
	v_mfma_f32_16x16x32_f16 v[4:7], v[156:159], v[218:221], v[4:7]
	v_mfma_f32_16x16x32_f16 v[0:3], v[186:189], v[218:221], v[0:3]
	v_mfma_f32_16x16x32_f16 v[48:51], v[190:193], v[206:209], v[32:35]
	v_mfma_f32_16x16x32_f16 v[20:23], v[168:171], v[214:217], v[20:23]
	v_mfma_f32_16x16x32_f16 v[16:19], v[190:193], v[214:217], v[16:19]
	v_mfma_f32_16x16x32_f16 v[4:7], v[168:171], v[222:225], v[4:7]
	v_mfma_f32_16x16x32_f16 v[0:3], v[190:193], v[222:225], v[0:3]
	s_setprio 0
	s_barrier
	s_add_i32 s61, s61, 2
	s_add_u32 s54, s54, 0x100
	s_addc_u32 s55, s55, 0
	s_add_u32 s49, s49, 0x100
	s_addc_u32 s60, s60, 0
	s_cmp_gt_u32 s61, 13
	s_cbranch_scc0 .LBB0_904
	s_and_b64 vcc, exec, s[44:45]
	s_cbranch_vccz .LBB0_907
	s_barrier

; #define PG8_STAGE(bufoff, gbase, voff) do { _Pragma("unroll") for (int _i = 0; _i < 2; ++_i) \
;         __builtin_amdgcn_global_load_lds((const unsigned*)((const char*)(gbase) + (voff)[_i]), (PG8_LAS unsigned*)(lds + (bufoff) + ldsw + _i * 8192), 16, 0, 0); } while (0)
; #define PG8_LDA(dst, b, h) do { _Pragma("unroll") for (int m = 0; m < 4; ++m) _Pragma("unroll") for (int k = 0; k < 2; ++k) dst[m][k] = *(const PG8_LAS bf16x8*)(lds + PG8_SA(b, h) + aoff + m * 2048 + k * 1024); } while (0)
; #define PG8_LDB(dst, b, h) do { _Pragma("unroll") for (int n = 0; n < 2; ++n) _Pragma("unroll") for (int k = 0; k < 2; ++k) dst[n][k] = *(const PG8_LAS bf16x8*)(lds + PG8_SB(b, h) + boff + n * 2048 + k * 1024); } while (0)
; #define PG8_MMA(ai, bj, At, Bt) do { __builtin_amdgcn_s_setprio(1); _Pragma("unroll") for (int m = 0; m < 4; ++m) _Pragma("unroll") for (int n = 0; n < 2; ++n) _Pragma("unroll") for (int k = 0; k < 2; ++k) \
;         acc[ai][bj][m][n] = mma16<F16>(Bt[n][k], At[m][k], acc[ai][bj][m][n]); __builtin_amdgcn_s_setprio(0); } while (0)
; #define PG8_WAIT_V(n) asm volatile("s_waitcnt vmcnt(" #n ")" ::: "memory")
; #define PG8_WAIT_L(n) asm volatile("s_waitcnt lgkmcnt(" #n ")" ::: "memory")
; #define PG8_BAR __builtin_amdgcn_s_barrier()
; #define PG8_SCHED __builtin_amdgcn_sched_barrier(0)
; template <class Epi, class Sched, bool ALIGN_EPI = false, bool SP2 = false, bool F16 = false>
; __device__ __forceinline__ void gemm_phase(PG8_LAS unsigned char* lds, const Gemm g, const Sched& S, const Epi& E) {
;     ...
;             const char* a1 = cA + (size_t)(t + 1) * kstep;
;             const char* a2 = last ? nA : cA + (size_t)(t + 2) * kstep; const char* b2 = last ? nB : cB + (size_t)(t + 2) * kstep;
;             const char* a3 = a2 + kstep; const char* b3 = b2 + kstep;
;             if (last && has_next) S.a_ready(nxt);
;             if constexpr (SP2) {
;             PG8_LDB(B0, 0, 0); PG8_LDB(B1, 0, 1); PG8_SCHED; PG8_LDA(At, 0, 0); PG8_STAGE(PG8_SA(1, 1), a1 + hstep, voffA);
;             PG8_WAIT_V(8); PG8_WAIT_L(0); PG8_BAR; PG8_MMA(0, 0, At, B0); PG8_MMA(0, 1, At, B1); PG8_BAR; PG8_SCHED;
;             PG8_LDA(At, 0, 1); PG8_STAGE(PG8_SB(0, 0), b2, voffB); PG8_STAGE(PG8_SB(0, 1), b2 + hstep, voffB); PG8_STAGE(PG8_SA(0, 0), a2, voffA);
;             PG8_WAIT_V(8); PG8_WAIT_L(0); PG8_BAR; PG8_MMA(1, 0, At, B0); PG8_MMA(1, 1, At, B1); PG8_BAR; PG8_SCHED;
.LBB0_997:
	s_add_u32 s50, s48, 0x100
	s_addc_u32 s51, s49, 0
	s_add_i32 s59, 0, 0x10000
	s_cmp_eq_u32 s58, 40
	s_cselect_b32 s55, s43, s51
	s_cselect_b32 s54, s42, s50
	s_cselect_b32 s53, s47, s5
	s_cselect_b32 s52, s46, s4
	s_add_i32 s60, 0, 0x14000
	ds_read_b128 v[130:133], v172
	ds_read_b128 v[134:137], v172 offset:1024
	ds_read_b128 v[138:141], v172 offset:2048
	ds_read_b128 v[142:145], v172 offset:3072
	ds_read_b128 v[146:149], v172 offset:16384
	ds_read_b128 v[150:153], v172 offset:17408
	ds_read_b128 v[154:157], v172 offset:18432
	ds_read_b128 v[158:161], v172 offset:19456
	s_add_i32 m0, s9, 0xc000
	ds_read_b128 v[186:189], v225
	ds_read_b128 v[190:193], v225 offset:1024
	ds_read_b128 v[194:197], v225 offset:2048
	ds_read_b128 v[198:201], v225 offset:3072
	ds_read_b128 v[202:205], v225 offset:4096
	ds_read_b128 v[206:209], v225 offset:5120
	ds_read_b128 v[210:213], v225 offset:6144
	ds_read_b128 v[214:217], v225 offset:7168
	global_load_lds_dwordx4 v168, s[48:49]
	s_add_i32 m0, s9, 0xe000
	s_nop 0
	global_load_lds_dwordx4 v170, s[48:49]
	s_waitcnt vmcnt(8) lgkmcnt(0)
	s_barrier
	s_setprio 1
	v_mfma_f32_16x16x32_bf16 v[124:127], v[130:133], v[186:189], v[124:127]
	v_mfma_f32_16x16x32_bf16 v[120:123], v[138:141], v[186:189], v[120:123]
	v_mfma_f32_16x16x32_bf16 v[116:119], v[130:133], v[194:197], v[116:119]
	v_mfma_f32_16x16x32_bf16 v[112:115], v[138:141], v[194:197], v[112:115]
	v_mfma_f32_16x16x32_bf16 v[108:111], v[130:133], v[202:205], v[108:111]
	v_mfma_f32_16x16x32_bf16 v[104:107], v[138:141], v[202:205], v[104:107]
	v_mfma_f32_16x16x32_bf16 v[100:103], v[130:133], v[210:213], v[100:103]
	v_mfma_f32_16x16x32_bf16 v[96:99], v[138:141], v[210:213], v[96:99]
	v_mfma_f32_16x16x32_bf16 v[124:127], v[134:137], v[190:193], v[124:127]
	v_mfma_f32_16x16x32_bf16 v[120:123], v[142:145], v[190:193], v[120:123]
	v_mfma_f32_16x16x32_bf16 v[116:119], v[134:137], v[198:201], v[116:119]
	v_mfma_f32_16x16x32_bf16 v[112:115], v[142:145], v[198:201], v[112:115]
	v_mfma_f32_16x16x32_bf16 v[108:111], v[134:137], v[206:209], v[108:111]
	v_mfma_f32_16x16x32_bf16 v[104:107], v[142:145], v[206:209], v[104:107]
	v_mfma_f32_16x16x32_bf16 v[100:103], v[134:137], v[214:217], v[100:103]
	v_mfma_f32_16x16x32_bf16 v[96:99], v[142:145], v[214:217], v[96:99]
	v_mfma_f32_16x16x32_bf16 v[60:63], v[146:149], v[186:189], v[60:63]
	v_mfma_f32_16x16x32_bf16 v[56:59], v[154:157], v[186:189], v[56:59]
	v_mfma_f32_16x16x32_bf16 v[52:55], v[146:149], v[194:197], v[52:55]
	v_mfma_f32_16x16x32_bf16 v[48:51], v[154:157], v[194:197], v[48:51]
	v_mfma_f32_16x16x32_bf16 v[44:47], v[146:149], v[202:205], v[44:47]
	v_mfma_f32_16x16x32_bf16 v[40:43], v[154:157], v[202:205], v[40:43]
	v_mfma_f32_16x16x32_bf16 v[36:39], v[146:149], v[210:213], v[36:39]
	v_mfma_f32_16x16x32_bf16 v[32:35], v[154:157], v[210:213], v[32:35]
	v_mfma_f32_16x16x32_bf16 v[60:63], v[150:153], v[190:193], v[60:63]
	v_mfma_f32_16x16x32_bf16 v[56:59], v[158:161], v[190:193], v[56:59]
	v_mfma_f32_16x16x32_bf16 v[52:55], v[150:153], v[198:201], v[52:55]
	v_mfma_f32_16x16x32_bf16 v[48:51], v[158:161], v[198:201], v[48:51]
	v_mfma_f32_16x16x32_bf16 v[44:47], v[150:153], v[206:209], v[44:47]
	v_mfma_f32_16x16x32_bf16 v[40:43], v[158:161], v[206:209], v[40:43]
	v_mfma_f32_16x16x32_bf16 v[36:39], v[150:153], v[214:217], v[36:39]
	v_mfma_f32_16x16x32_bf16 v[32:35], v[158:161], v[214:217], v[32:35]
	s_setprio 0
	s_barrier
	s_add_u32 s98, s52, s16
	s_addc_u32 s99, s53, s17
	s_add_u32 s100, s54, s16
	s_addc_u32 s101, s55, s17
	s_add_i32 s48, s59, s8
	s_mov_b32 m0, s48
	ds_read_b128 v[186:189], v225 offset:16384
	ds_read_b128 v[190:193], v225 offset:17408
	ds_read_b128 v[194:197], v225 offset:18432
	ds_read_b128 v[198:201], v225 offset:19456
	ds_read_b128 v[202:205], v225 offset:20480
	ds_read_b128 v[206:209], v225 offset:21504
	ds_read_b128 v[210:213], v225 offset:22528
	ds_read_b128 v[214:217], v225 offset:23552
	global_load_lds_dwordx4 v128, s[52:53]
	s_add_i32 m0, s48, 0x2000
	s_add_u32 s48, s52, 0xb0000
	s_addc_u32 s49, s53, 0
	s_add_i32 s59, s60, s8
	global_load_lds_dwordx4 v162, s[52:53]
	s_mov_b32 m0, s59
	s_nop 0
	global_load_lds_dwordx4 v128, s[48:49]
	s_add_i32 m0, s59, 0x2000
	s_nop 0
	global_load_lds_dwordx4 v162, s[48:49]
	s_mov_b32 m0, s9
	s_nop 0
	global_load_lds_dwordx4 v166, s[54:55]
	s_mov_b32 m0, s10
	s_nop 0
	global_load_lds_dwordx4 v164, s[54:55]
	s_waitcnt vmcnt(8) lgkmcnt(0)
	s_barrier
	s_setprio 1
	v_mfma_f32_16x16x32_bf16 v[92:95], v[130:133], v[186:189], v[92:95]
	v_mfma_f32_16x16x32_bf16 v[88:91], v[138:141], v[186:189], v[88:91]
	v_mfma_f32_16x16x32_bf16 v[84:87], v[130:133], v[194:197], v[84:87]
	v_mfma_f32_16x16x32_bf16 v[80:83], v[138:141], v[194:197], v[80:83]
	v_mfma_f32_16x16x32_bf16 v[76:79], v[130:133], v[202:205], v[76:79]
	v_mfma_f32_16x16x32_bf16 v[72:75], v[138:141], v[202:205], v[72:75]
	v_mfma_f32_16x16x32_bf16 v[68:71], v[130:133], v[210:213], v[68:71]
	v_mfma_f32_16x16x32_bf16 v[64:67], v[138:141], v[210:213], v[64:67]
	v_mfma_f32_16x16x32_bf16 v[92:95], v[134:137], v[190:193], v[92:95]
	v_mfma_f32_16x16x32_bf16 v[88:91], v[142:145], v[190:193], v[88:91]
	v_mfma_f32_16x16x32_bf16 v[84:87], v[134:137], v[198:201], v[84:87]
	v_mfma_f32_16x16x32_bf16 v[80:83], v[142:145], v[198:201], v[80:83]
	v_mfma_f32_16x16x32_bf16 v[76:79], v[134:137], v[206:209], v[76:79]
	v_mfma_f32_16x16x32_bf16 v[72:75], v[142:145], v[206:209], v[72:75]
	v_mfma_f32_16x16x32_bf16 v[68:71], v[134:137], v[214:217], v[68:71]
	v_mfma_f32_16x16x32_bf16 v[64:67], v[142:145], v[214:217], v[64:67]
	v_mfma_f32_16x16x32_bf16 v[28:31], v[146:149], v[186:189], v[28:31]
	v_mfma_f32_16x16x32_bf16 v[24:27], v[154:157], v[186:189], v[24:27]
	v_mfma_f32_16x16x32_bf16 v[20:23], v[146:149], v[194:197], v[20:23]
	v_mfma_f32_16x16x32_bf16 v[16:19], v[154:157], v[194:197], v[16:19]
	v_mfma_f32_16x16x32_bf16 v[12:15], v[146:149], v[202:205], v[12:15]
	v_mfma_f32_16x16x32_bf16 v[8:11], v[154:157], v[202:205], v[8:11]
	v_mfma_f32_16x16x32_bf16 v[4:7], v[146:149], v[210:213], v[4:7]
	v_mfma_f32_16x16x32_bf16 v[0:3], v[154:157], v[210:213], v[0:3]
	v_mfma_f32_16x16x32_bf16 v[28:31], v[150:153], v[190:193], v[28:31]
	v_mfma_f32_16x16x32_bf16 v[24:27], v[158:161], v[190:193], v[24:27]
	v_mfma_f32_16x16x32_bf16 v[20:23], v[150:153], v[198:201], v[20:23]
	v_mfma_f32_16x16x32_bf16 v[16:19], v[158:161], v[198:201], v[16:19]
	v_mfma_f32_16x16x32_bf16 v[12:15], v[150:153], v[206:209], v[12:15]
	v_mfma_f32_16x16x32_bf16 v[8:11], v[158:161], v[206:209], v[8:11]
	v_mfma_f32_16x16x32_bf16 v[4:7], v[150:153], v[214:217], v[4:7]
	v_mfma_f32_16x16x32_bf16 v[0:3], v[158:161], v[214:217], v[0:3]
	s_setprio 0
	s_barrier
; #define PG8_STAGE(bufoff, gbase, voff) do { _Pragma("unroll") for (int _i = 0; _i < 2; ++_i) \
;         __builtin_amdgcn_global_load_lds((const unsigned*)((const char*)(gbase) + (voff)[_i]), (PG8_LAS unsigned*)(lds + (bufoff) + ldsw + _i * 8192), 16, 0, 0); } while (0)
; #define PG8_LDA(dst, b, h) do { _Pragma("unroll") for (int m = 0; m < 4; ++m) _Pragma("unroll") for (int k = 0; k < 2; ++k) dst[m][k] = *(const PG8_LAS bf16x8*)(lds + PG8_SA(b, h) + aoff + m * 2048 + k * 1024); } while (0)
; #define PG8_LDB(dst, b, h) do { _Pragma("unroll") for (int n = 0; n < 2; ++n) _Pragma("unroll") for (int k = 0; k < 2; ++k) dst[n][k] = *(const PG8_LAS bf16x8*)(lds + PG8_SB(b, h) + boff + n * 2048 + k * 1024); } while (0)
; #define PG8_MMA(ai, bj, At, Bt) do { __builtin_amdgcn_s_setprio(1); _Pragma("unroll") for (int m = 0; m < 4; ++m) _Pragma("unroll") for (int n = 0; n < 2; ++n) _Pragma("unroll") for (int k = 0; k < 2; ++k) \
;         acc[ai][bj][m][n] = mma16<F16>(Bt[n][k], At[m][k], acc[ai][bj][m][n]); __builtin_amdgcn_s_setprio(0); } while (0)
; #define PG8_WAIT_V(n) asm volatile("s_waitcnt vmcnt(" #n ")" ::: "memory")
; #define PG8_WAIT_L(n) asm volatile("s_waitcnt lgkmcnt(" #n ")" ::: "memory")
; #define PG8_BAR __builtin_amdgcn_s_barrier()
; #define PG8_SCHED __builtin_amdgcn_sched_barrier(0)
; template <class Epi, class Sched, bool ALIGN_EPI = false, bool SP2 = false, bool F16 = false>
; __device__ __forceinline__ void gemm_phase(PG8_LAS unsigned char* lds, const Gemm g, const Sched& S, const Epi& E) {
;     ...
;             PG8_LDB(B0, 1, 0); PG8_LDB(B1, 1, 1); PG8_SCHED; PG8_LDA(At, 1, 0); PG8_STAGE(PG8_SA(0, 1), a2 + hstep, voffA);
;             PG8_WAIT_V(8); PG8_WAIT_L(0); PG8_BAR; PG8_MMA(0, 0, At, B0); PG8_MMA(0, 1, At, B1); PG8_BAR; PG8_SCHED;
;             PG8_LDA(At, 1, 1); PG8_STAGE(PG8_SB(1, 0), b3, voffB); PG8_STAGE(PG8_SB(1, 1), b3 + hstep, voffB); PG8_STAGE(PG8_SA(1, 0), a3, voffA);
;             PG8_WAIT_V(8); PG8_WAIT_L(0); PG8_BAR; PG8_MMA(1, 0, At, B0); PG8_MMA(1, 1, At, B1); PG8_BAR; PG8_SCHED;
	s_add_i32 s59, 0, 0x18000
	s_add_i32 s60, 0, 0x1c000
	ds_read_b128 v[130:133], v172 offset:32768
	ds_read_b128 v[134:137], v172 offset:33792
	ds_read_b128 v[138:141], v172 offset:34816
	ds_read_b128 v[142:145], v172 offset:35840
	ds_read_b128 v[146:149], v172 offset:49152
	ds_read_b128 v[150:153], v172 offset:50176
	ds_read_b128 v[154:157], v172 offset:51200
	ds_read_b128 v[158:161], v172 offset:52224
	s_add_u32 s48, s54, 0xb0000
	s_addc_u32 s49, s55, 0
	s_mov_b32 m0, s11
	ds_read_b128 v[186:189], v225 offset:32768
	ds_read_b128 v[190:193], v225 offset:33792
	ds_read_b128 v[194:197], v225 offset:34816
	ds_read_b128 v[198:201], v225 offset:35840
	ds_read_b128 v[202:205], v225 offset:36864
	ds_read_b128 v[206:209], v225 offset:37888
	ds_read_b128 v[210:213], v225 offset:38912
	ds_read_b128 v[214:217], v225 offset:39936
	global_load_lds_dwordx4 v166, s[48:49]
	s_mov_b32 m0, s14
	s_nop 0
	global_load_lds_dwordx4 v164, s[48:49]
	s_waitcnt vmcnt(8) lgkmcnt(0)
	s_barrier
	s_setprio 1
	v_mfma_f32_16x16x32_bf16 v[124:127], v[130:133], v[186:189], v[124:127]
	v_mfma_f32_16x16x32_bf16 v[120:123], v[138:141], v[186:189], v[120:123]
	v_mfma_f32_16x16x32_bf16 v[116:119], v[130:133], v[194:197], v[116:119]
	v_mfma_f32_16x16x32_bf16 v[112:115], v[138:141], v[194:197], v[112:115]
	v_mfma_f32_16x16x32_bf16 v[108:111], v[130:133], v[202:205], v[108:111]
	v_mfma_f32_16x16x32_bf16 v[104:107], v[138:141], v[202:205], v[104:107]
	v_mfma_f32_16x16x32_bf16 v[100:103], v[130:133], v[210:213], v[100:103]
	v_mfma_f32_16x16x32_bf16 v[96:99], v[138:141], v[210:213], v[96:99]
	v_mfma_f32_16x16x32_bf16 v[124:127], v[134:137], v[190:193], v[124:127]
	v_mfma_f32_16x16x32_bf16 v[120:123], v[142:145], v[190:193], v[120:123]
	v_mfma_f32_16x16x32_bf16 v[116:119], v[134:137], v[198:201], v[116:119]
	v_mfma_f32_16x16x32_bf16 v[112:115], v[142:145], v[198:201], v[112:115]
	v_mfma_f32_16x16x32_bf16 v[108:111], v[134:137], v[206:209], v[108:111]
	v_mfma_f32_16x16x32_bf16 v[104:107], v[142:145], v[206:209], v[104:107]
	v_mfma_f32_16x16x32_bf16 v[100:103], v[134:137], v[214:217], v[100:103]
	v_mfma_f32_16x16x32_bf16 v[96:99], v[142:145], v[214:217], v[96:99]
	v_mfma_f32_16x16x32_bf16 v[60:63], v[146:149], v[186:189], v[60:63]
	v_mfma_f32_16x16x32_bf16 v[56:59], v[154:157], v[186:189], v[56:59]
	v_mfma_f32_16x16x32_bf16 v[52:55], v[146:149], v[194:197], v[52:55]
	v_mfma_f32_16x16x32_bf16 v[48:51], v[154:157], v[194:197], v[48:51]
	v_mfma_f32_16x16x32_bf16 v[44:47], v[146:149], v[202:205], v[44:47]
	v_mfma_f32_16x16x32_bf16 v[40:43], v[154:157], v[202:205], v[40:43]
	v_mfma_f32_16x16x32_bf16 v[36:39], v[146:149], v[210:213], v[36:39]
	v_mfma_f32_16x16x32_bf16 v[32:35], v[154:157], v[210:213], v[32:35]
	v_mfma_f32_16x16x32_bf16 v[60:63], v[150:153], v[190:193], v[60:63]
	v_mfma_f32_16x16x32_bf16 v[56:59], v[158:161], v[190:193], v[56:59]
	v_mfma_f32_16x16x32_bf16 v[52:55], v[150:153], v[198:201], v[52:55]
	v_mfma_f32_16x16x32_bf16 v[48:51], v[158:161], v[198:201], v[48:51]
	v_mfma_f32_16x16x32_bf16 v[44:47], v[150:153], v[206:209], v[44:47]
	v_mfma_f32_16x16x32_bf16 v[40:43], v[158:161], v[206:209], v[40:43]
	v_mfma_f32_16x16x32_bf16 v[36:39], v[150:153], v[214:217], v[36:39]
	v_mfma_f32_16x16x32_bf16 v[32:35], v[158:161], v[214:217], v[32:35]
	s_setprio 0
	s_barrier
	s_add_i32 s48, s59, s8
	s_mov_b32 m0, s48
	ds_read_b128 v[186:189], v225 offset:49152
	ds_read_b128 v[190:193], v225 offset:50176
	ds_read_b128 v[194:197], v225 offset:51200
	ds_read_b128 v[198:201], v225 offset:52224
	ds_read_b128 v[202:205], v225 offset:53248
	ds_read_b128 v[206:209], v225 offset:54272
	ds_read_b128 v[210:213], v225 offset:55296
	ds_read_b128 v[214:217], v225 offset:56320
	global_load_lds_dwordx4 v128, s[98:99]
	s_add_i32 m0, s48, 0x2000
	s_add_u32 s48, s52, 0xb0080
	s_addc_u32 s49, s53, 0
	s_add_i32 s52, s60, s8
	global_load_lds_dwordx4 v162, s[98:99]
	s_mov_b32 m0, s52
	s_nop 0
	global_load_lds_dwordx4 v128, s[48:49]
	s_add_i32 m0, s52, 0x2000
	s_nop 0
	global_load_lds_dwordx4 v162, s[48:49]
	s_mov_b32 m0, s29
	s_nop 0
	global_load_lds_dwordx4 v166, s[100:101]
	s_mov_b32 m0, s30
	s_nop 0
	global_load_lds_dwordx4 v164, s[100:101]
	s_waitcnt vmcnt(8) lgkmcnt(0)
	s_barrier
	s_setprio 1
	v_mfma_f32_16x16x32_bf16 v[92:95], v[130:133], v[186:189], v[92:95]
	v_mfma_f32_16x16x32_bf16 v[88:91], v[138:141], v[186:189], v[88:91]
	v_mfma_f32_16x16x32_bf16 v[84:87], v[130:133], v[194:197], v[84:87]
	v_mfma_f32_16x16x32_bf16 v[80:83], v[138:141], v[194:197], v[80:83]
	v_mfma_f32_16x16x32_bf16 v[76:79], v[130:133], v[202:205], v[76:79]
	v_mfma_f32_16x16x32_bf16 v[72:75], v[138:141], v[202:205], v[72:75]
	v_mfma_f32_16x16x32_bf16 v[68:71], v[130:133], v[210:213], v[68:71]
	v_mfma_f32_16x16x32_bf16 v[64:67], v[138:141], v[210:213], v[64:67]
	v_mfma_f32_16x16x32_bf16 v[92:95], v[134:137], v[190:193], v[92:95]
	v_mfma_f32_16x16x32_bf16 v[88:91], v[142:145], v[190:193], v[88:91]
	v_mfma_f32_16x16x32_bf16 v[84:87], v[134:137], v[198:201], v[84:87]
	v_mfma_f32_16x16x32_bf16 v[80:83], v[142:145], v[198:201], v[80:83]
	v_mfma_f32_16x16x32_bf16 v[76:79], v[134:137], v[206:209], v[76:79]
	v_mfma_f32_16x16x32_bf16 v[72:75], v[142:145], v[206:209], v[72:75]
	v_mfma_f32_16x16x32_bf16 v[68:71], v[134:137], v[214:217], v[68:71]
	v_mfma_f32_16x16x32_bf16 v[64:67], v[142:145], v[214:217], v[64:67]
	v_mfma_f32_16x16x32_bf16 v[28:31], v[146:149], v[186:189], v[28:31]
	v_mfma_f32_16x16x32_bf16 v[24:27], v[154:157], v[186:189], v[24:27]
	v_mfma_f32_16x16x32_bf16 v[20:23], v[146:149], v[194:197], v[20:23]
	v_mfma_f32_16x16x32_bf16 v[16:19], v[154:157], v[194:197], v[16:19]
	v_mfma_f32_16x16x32_bf16 v[12:15], v[146:149], v[202:205], v[12:15]
	v_mfma_f32_16x16x32_bf16 v[8:11], v[154:157], v[202:205], v[8:11]
	v_mfma_f32_16x16x32_bf16 v[4:7], v[146:149], v[210:213], v[4:7]
	v_mfma_f32_16x16x32_bf16 v[0:3], v[154:157], v[210:213], v[0:3]
	v_mfma_f32_16x16x32_bf16 v[28:31], v[150:153], v[190:193], v[28:31]
	v_mfma_f32_16x16x32_bf16 v[24:27], v[158:161], v[190:193], v[24:27]
	v_mfma_f32_16x16x32_bf16 v[20:23], v[150:153], v[198:201], v[20:23]
	v_mfma_f32_16x16x32_bf16 v[16:19], v[158:161], v[198:201], v[16:19]
	v_mfma_f32_16x16x32_bf16 v[12:15], v[150:153], v[206:209], v[12:15]
	v_mfma_f32_16x16x32_bf16 v[8:11], v[158:161], v[206:209], v[8:11]
	v_mfma_f32_16x16x32_bf16 v[4:7], v[150:153], v[214:217], v[4:7]
	v_mfma_f32_16x16x32_bf16 v[0:3], v[158:161], v[214:217], v[0:3]
	s_setprio 0
	s_barrier
	s_add_i32 s58, s58, 2
	s_add_u32 s4, s4, 0x100
	s_addc_u32 s5, s5, 0
	s_cmp_gt_u32 s58, 41
	s_mov_b64 s[48:49], s[50:51]
	s_cbranch_scc0 .LBB0_997
	s_and_b64 vcc, exec, s[44:45]
	s_cbranch_vccz .LBB0_1000
	s_barrier
